# attention: exp2 scale folded into the packed score negation and the clamp constant (one VALU multiply per score removed; bit-identical)
# speedup vs baseline: 1.0040x; 1.0020x over previous
; __device__ __forceinline__ float fexp(float x) { return __builtin_amdgcn_exp2f(x * 1.44269504f); }
; __device__ __forceinline__ void item_attn(const Params& p, int l, int aidx) {
;     ...
;       for (int m = 0; m < 4; ++m) {
;         bf16x8 a0 = *reinterpret_cast<const bf16x8*>(Ks + (m * 16 + fr) * 72 + fq * 8);
;         bf16x8 a1 = *reinterpret_cast<const bf16x8*>(Ks + (m * 16 + fr) * 72 + 32 + fq * 8);
; #pragma unroll
;         for (int n = 0; n < 2; ++n) {
;           f32x4 zz = f32x4{0.f, 0.f, 0.f, 0.f};
;           zz = __builtin_amdgcn_mfma_f32_16x16x32_bf16(a0, qf[n][0], zz, 0, 0, 0);
;           zz = __builtin_amdgcn_mfma_f32_16x16x32_bf16(a1, qf[n][1], zz, 0, 0, 0);
;           z[m][n] = zz;
;         }
;       }
;       unsigned pk[4][2][2];
;       auto sb_weights = [&](auto MASKED) {
; #pragma unroll
;         for (int n = 0; n < 2; ++n) {
;           const int qpos = qpos0 + 32 * wid + 16 * n + fr;
;           float wgt[4][4], excl[4][4], later[4], TT[4];
; #pragma unroll
;           for (int m = 0; m < 4; ++m) {
;             float f[4];
; #pragma unroll
;             for (int j = 0; j < 4; ++j) {
;               const float e = fexp(fminf(-z[m][n][j], 80.f));
;               const float sg = __builtin_amdgcn_rcpf(1.f + e);
;               if (decltype(MASKED)::value) {
;                 const bool ok = (kt * 64 + m * 16 + fq * 4 + j) < qpos;
;                 wgt[m][j] = ok ? sg : 0.f;
;                 f[j] = ok ? e * sg : 1.f;
;               } else { wgt[m][j] = sg; f[j] = e * sg; }
;             }
.LBB0_687:
	s_xor_b64 s[0:1], s[0:1], -1
	s_andn2_b64 vcc, exec, s[0:1]
	s_mov_b64 s[0:1], -1
	s_cbranch_vccnz .LBB0_694
	s_cmp_ge_i32 s24, s51
	s_mov_b64 s[0:1], 0
	s_cbranch_scc1 .LBB0_694
	ds_read_b128 v[64:67], v118
	ds_read_b128 v[68:71], v118 offset:64
	s_mov_b32 s100, 0xbfb8aa3b
	s_nop 0
	s_nop 0
	s_waitcnt lgkmcnt(1)
	v_mfma_f32_16x16x32_bf16 v[72:75], v[64:67], v[4:7], 0
	s_nop 0
	s_add_i32 s0, s49, 0x7f
	s_cmp_ge_i32 s0, s50
	v_mfma_f32_16x16x32_bf16 v[64:67], v[64:67], v[12:15], 0
	s_nop 0
	s_nop 0
	s_nop 0
	s_waitcnt lgkmcnt(0)
	v_mfma_f32_16x16x32_bf16 v[72:75], v[68:71], v[0:3], v[72:75]
	s_nop 0
	s_mov_b64 s[0:1], -1
	v_mfma_f32_16x16x32_bf16 v[64:67], v[68:71], v[8:11], v[64:67]
	ds_read_b128 v[68:71], v118 offset:2304
	ds_read_b128 v[76:79], v118 offset:2368
	s_nop 0
	s_nop 1
	s_nop 0
	s_waitcnt lgkmcnt(1)
	v_mfma_f32_16x16x32_bf16 v[92:95], v[68:71], v[4:7], 0
	v_pk_mul_f32 v[160:161], v[72:73], s[100:101] op_sel_hi:[1,0]
	s_nop 0
	v_pk_mul_f32 v[158:159], v[74:75], s[100:101] op_sel:[1,0] op_sel_hi:[0,0]
	v_mfma_f32_16x16x32_bf16 v[68:71], v[68:71], v[12:15], 0
	s_nop 0
	v_pk_mul_f32 v[144:145], v[64:65], s[100:101] op_sel:[1,0] op_sel_hi:[0,0]
	s_nop 0
	s_waitcnt lgkmcnt(0)
	v_mfma_f32_16x16x32_bf16 v[92:95], v[76:79], v[0:3], v[92:95]
	v_pk_mul_f32 v[142:143], v[66:67], s[100:101] op_sel_hi:[1,0]
	v_mfma_f32_16x16x32_bf16 v[68:71], v[76:79], v[8:11], v[68:71]
	ds_read_b128 v[76:79], v118 offset:4608
	ds_read_b128 v[96:99], v118 offset:4672
	s_nop 3
	s_nop 0
	v_pk_mul_f32 v[156:157], v[92:93], s[100:101] op_sel:[1,0] op_sel_hi:[0,0]
	s_waitcnt lgkmcnt(1)
	v_mfma_f32_16x16x32_bf16 v[128:131], v[76:79], v[4:7], 0
	s_nop 0
	v_pk_mul_f32 v[154:155], v[94:95], s[100:101] op_sel_hi:[1,0]
	v_mfma_f32_16x16x32_bf16 v[76:79], v[76:79], v[12:15], 0
	s_waitcnt lgkmcnt(0)
	v_mfma_f32_16x16x32_bf16 v[130:133], v[96:99], v[0:3], v[128:131]
	v_mfma_f32_16x16x32_bf16 v[76:79], v[96:99], v[8:11], v[76:79]
	ds_read_b128 v[96:99], v118 offset:6912
	ds_read_b128 v[134:137], v118 offset:6976
	s_nop 0
	s_nop 0
	s_waitcnt lgkmcnt(1)
	v_mfma_f32_16x16x32_bf16 v[138:141], v[96:99], v[4:7], 0
	s_nop 0
	v_mul_f32_e32 v151, s100, v130
	v_mul_f32_e32 v153, s100, v131
	v_mfma_f32_16x16x32_bf16 v[96:99], v[96:99], v[12:15], 0
	s_nop 0
	s_nop 0
	v_mul_f32_e32 v152, s100, v132
	s_waitcnt lgkmcnt(0)
	v_mfma_f32_16x16x32_bf16 v[138:141], v[134:137], v[0:3], v[138:141]
	v_mul_f32_e32 v150, s100, v133
	v_mfma_f32_16x16x32_bf16 v[96:99], v[134:137], v[8:11], v[96:99]
	s_nop 0
	s_nop 4
	v_mul_f32_e32 v147, s100, v138
	v_mul_f32_e32 v149, s100, v139
	v_mul_f32_e32 v148, s100, v140
	v_mul_f32_e32 v146, s100, v141
	s_nop 0
	v_pk_mul_f32 v[140:141], v[68:69], s[100:101] op_sel:[1,0] op_sel_hi:[0,0]
	s_nop 0
	v_pk_mul_f32 v[138:139], v[70:71], s[100:101] op_sel:[1,0] op_sel_hi:[0,0]
	v_pk_mul_f32 v[136:137], v[76:77], s[100:101] op_sel:[1,0] op_sel_hi:[0,0]
	s_nop 0
	v_pk_mul_f32 v[134:135], v[78:79], s[100:101] op_sel:[1,0] op_sel_hi:[0,0]
	s_nop 0
	v_pk_mul_f32 v[132:133], v[96:97], s[100:101] op_sel_hi:[1,0]
	s_nop 0
	v_pk_mul_f32 v[130:131], v[98:99], s[100:101] op_sel:[1,0] op_sel_hi:[0,0]
	s_cbranch_scc0 .LBB0_691
	v_min_f32_e32 v64, 0x42e6d4ca, v160
	v_min_f32_e32 v65, 0x42e6d4ca, v161
	v_exp_f32_e32 v67, v64
	v_exp_f32_e32 v69, v65
	v_min_f32_e32 v65, 0x42e6d4ca, v159
	v_exp_f32_e32 v65, v65
	v_min_f32_e32 v68, 0x42e6d4ca, v157
	v_add_f32_e32 v66, 1.0, v67
	v_rcp_f32_e32 v73, v66
	v_add_f32_e32 v66, 1.0, v69
	v_exp_f32_e32 v68, v68
	v_rcp_f32_e32 v75, v66
	v_add_f32_e32 v66, 1.0, v65
	v_rcp_f32_e32 v77, v66
	v_min_f32_e32 v66, 0x42e6d4ca, v158
	v_min_f32_e32 v70, 0x42e6d4ca, v156
	v_exp_f32_e32 v71, v66
	v_add_f32_e32 v66, 1.0, v68
	v_rcp_f32_e32 v66, v66
	v_exp_f32_e32 v70, v70
	v_add_u32_e32 v64, s49, v114
	v_add_u32_e32 v180, 0x50, v64
	v_cmp_lt_i32_e32 vcc, v180, v85
	v_min_f32_e32 v74, 0x42e6d4ca, v154
	s_nop 0
	v_cndmask_b32_e32 v72, 0, v66, vcc
	v_mul_f32_e32 v66, v68, v66
	v_add_f32_e32 v68, 1.0, v70
	v_rcp_f32_e32 v68, v68
	v_exp_f32_e32 v74, v74
	v_add_u32_e32 v181, 0x51, v64
	v_cndmask_b32_e32 v66, 1.0, v66, vcc
	v_cmp_lt_i32_e32 vcc, v181, v85
	v_min_f32_e32 v78, 0x42e6d4ca, v155
	s_nop 0
	v_cndmask_b32_e32 v76, 0, v68, vcc
	v_mul_f32_e32 v68, v70, v68
	v_add_f32_e32 v70, 1.0, v74
	v_rcp_f32_e32 v70, v70
	v_exp_f32_e32 v78, v78
	v_add_u32_e32 v182, 0x52, v64
	v_cndmask_b32_e32 v68, 1.0, v68, vcc
	v_cmp_lt_i32_e32 vcc, v182, v85
	v_add_u32_e32 v183, 0x53, v64
	v_min_f32_e32 v98, 0x42e6d4ca, v153
	v_cndmask_b32_e32 v92, 0, v70, vcc
	v_mul_f32_e32 v70, v74, v70
	v_add_f32_e32 v74, 1.0, v78
	v_rcp_f32_e32 v74, v74
	v_cndmask_b32_e32 v70, 1.0, v70, vcc
	v_cmp_lt_i32_e32 vcc, v183, v85
	v_exp_f32_e32 v98, v98
	s_nop 0
	v_cndmask_b32_e32 v101, 0, v74, vcc
	v_mul_f32_e32 v74, v78, v74
	v_cndmask_b32_e32 v94, 1.0, v74, vcc
	v_mul_f32_e32 v70, v94, v70
	v_mul_f32_e32 v68, v68, v70
	v_mul_f32_e32 v66, v66, v68
	ds_bpermute_b32 v74, v241, v66
	ds_bpermute_b32 v78, v242, v66
	ds_bpermute_b32 v95, v243, v66
	v_add_u32_e32 v184, 0x60, v64
	v_cmp_lt_i32_e32 vcc, v184, v85
	s_waitcnt lgkmcnt(2)
	v_cndmask_b32_e64 v93, 1.0, v74, s[14:15]
	s_waitcnt lgkmcnt(1)
	v_cndmask_b32_e64 v96, 1.0, v78, s[16:17]
	v_mul_f32_e32 v93, v93, v96
	v_min_f32_e32 v96, 0x42e6d4ca, v151
	v_exp_f32_e32 v96, v96
	s_waitcnt lgkmcnt(0)
; __device__ __forceinline__ float fexp(float x) { return __builtin_amdgcn_exp2f(x * 1.44269504f); }
; __device__ __forceinline__ unsigned pack2(float a, float b) { unsigned r; asm volatile("v_cvt_pk_bf16_f32 %0, %1, %2" : "=v"(r) : "v"(a), "v"(b)); return r; }
; __device__ __forceinline__ void item_attn(const Params& p, int l, int aidx) {
;     ...
;             float f[4];
; #pragma unroll
;             for (int j = 0; j < 4; ++j) {
;               const float e = fexp(fminf(-z[m][n][j], 80.f));
;               const float sg = __builtin_amdgcn_rcpf(1.f + e);
;               if (decltype(MASKED)::value) {
;                 const bool ok = (kt * 64 + m * 16 + fq * 4 + j) < qpos;
;                 wgt[m][j] = ok ? sg : 0.f;
;                 f[j] = ok ? e * sg : 1.f;
;               } else { wgt[m][j] = sg; f[j] = e * sg; }
;             }
;             excl[m][3] = 1.f; excl[m][2] = f[3]; excl[m][1] = f[3] * f[2]; excl[m][0] = excl[m][1] * f[1];
;             const float G = excl[m][0] * f[0];
;             const float g1 = __shfl_xor(G, 16), g2 = __shfl_xor(G, 32), g3 = __shfl_xor(G, 48);
;             later[m] = ((fq ^ 1) > fq ? g1 : 1.f) * ((fq ^ 2) > fq ? g2 : 1.f) * ((fq ^ 3) > fq ? g3 : 1.f);
;             TT[m] = (G * g1) * (g2 * g3);
;           }
;           float lm[4]; lm[3] = carry[n]; lm[2] = lm[3] * TT[3]; lm[1] = lm[2] * TT[2]; lm[0] = lm[1] * TT[1];
; #pragma unroll
;           for (int m = 0; m < 4; ++m) {
;             const float base = later[m] * lm[m];
;             float pv[4];
; #pragma unroll
;             for (int j = 0; j < 4; ++j) pv[j] = wgt[m][j] * excl[m][j] * base;
;             pk[m][n][0] = pack2(pv[0], pv[1]); pk[m][n][1] = pack2(pv[2], pv[3]);
;           }
;           carry[n] = lm[0] * TT[0];
	v_cndmask_b32_e64 v97, 1.0, v95, s[18:19]
	v_mul_f32_e32 v93, v97, v93
	v_min_f32_e32 v99, 0x42e6d4ca, v152
	v_add_f32_e32 v97, 1.0, v96
	v_rcp_f32_e32 v97, v97
	v_exp_f32_e32 v99, v99
	v_add_u32_e32 v185, 0x61, v64
	v_cndmask_b32_e32 v169, 0, v97, vcc
	v_mul_f32_e32 v96, v96, v97
	v_add_f32_e32 v97, 1.0, v98
	v_rcp_f32_e32 v97, v97
	v_cndmask_b32_e32 v96, 1.0, v96, vcc
	v_cmp_lt_i32_e32 vcc, v185, v85
	v_add_u32_e32 v187, 0x62, v64
	v_mul_f32_e32 v164, v78, v95
	v_cndmask_b32_e32 v186, 0, v97, vcc
	v_mul_f32_e32 v97, v98, v97
	v_add_f32_e32 v98, 1.0, v99
	v_rcp_f32_e32 v100, v98
	v_min_f32_e32 v98, 0x42e6d4ca, v150
	v_exp_f32_e32 v162, v98
	v_cndmask_b32_e32 v97, 1.0, v97, vcc
	v_cmp_lt_i32_e32 vcc, v187, v85
	v_mul_f32_e32 v99, v99, v100
	v_min_f32_e32 v78, 0x42e6d4ca, v147
	v_cndmask_b32_e32 v98, 0, v100, vcc
	v_add_f32_e32 v100, 1.0, v162
	v_rcp_f32_e32 v100, v100
	v_add_u32_e32 v199, 0x63, v64
	v_cndmask_b32_e32 v99, 1.0, v99, vcc
	v_cmp_lt_i32_e32 vcc, v199, v85
	v_exp_f32_e32 v78, v78
	v_add_u32_e32 v203, 0x70, v64
	v_cndmask_b32_e32 v200, 0, v100, vcc
	v_mul_f32_e32 v100, v162, v100
	v_cndmask_b32_e32 v100, 1.0, v100, vcc
	v_mul_f32_e32 v201, v100, v99
	v_min_f32_e32 v99, 0x42e6d4ca, v149
	v_add_f32_e32 v95, 1.0, v78
	v_rcp_f32_e32 v95, v95
	v_exp_f32_e32 v99, v99
	v_cmp_lt_i32_e32 vcc, v203, v85
	v_min_f32_e32 v165, 0x42e6d4ca, v148
	v_mul_f32_e32 v78, v78, v95
	v_cndmask_b32_e32 v204, 0, v95, vcc
	v_add_f32_e32 v95, 1.0, v99
	v_rcp_f32_e32 v95, v95
	v_exp_f32_e32 v165, v165
	v_add_u32_e32 v205, 0x71, v64
	v_cndmask_b32_e32 v78, 1.0, v78, vcc
	v_cmp_lt_i32_e32 vcc, v205, v85
	v_min_f32_e32 v167, 0x42e6d4ca, v146
	s_nop 0
	v_cndmask_b32_e32 v206, 0, v95, vcc
	v_mul_f32_e32 v95, v99, v95
	v_add_f32_e32 v99, 1.0, v165
	v_rcp_f32_e32 v99, v99
	v_exp_f32_e32 v167, v167
	v_add_u32_e32 v207, 0x72, v64
	v_cndmask_b32_e32 v95, 1.0, v95, vcc
	v_cmp_lt_i32_e32 vcc, v207, v85
	v_add_u32_e32 v218, 0x73, v64
	v_add_u32_e32 v178, 64, v64
	v_cndmask_b32_e32 v168, 0, v99, vcc
	v_mul_f32_e32 v99, v165, v99
	v_add_f32_e32 v165, 1.0, v167
	v_rcp_f32_e32 v165, v165
	v_cndmask_b32_e32 v99, 1.0, v99, vcc
	v_cmp_lt_i32_e32 vcc, v218, v85
	v_add_u32_e32 v179, 0x41, v64
	v_mul_f32_e32 v202, v97, v201
	v_cndmask_b32_e32 v64, 0, v165, vcc
	v_mul_f32_e32 v165, v167, v165
	v_cndmask_b32_e32 v170, 1.0, v165, vcc
	v_mul_f32_e32 v97, v96, v202
	v_mul_f32_e32 v219, v170, v99
	ds_bpermute_b32 v163, v241, v97
	ds_bpermute_b32 v96, v242, v97
	v_mul_f32_e32 v220, v95, v219
	ds_bpermute_b32 v166, v243, v97
	v_mul_f32_e32 v172, v78, v220
	ds_bpermute_b32 v173, v242, v172
	ds_bpermute_b32 v174, v241, v172
	ds_bpermute_b32 v175, v243, v172
	v_mul_f32_e32 v162, v66, v74
	s_waitcnt lgkmcnt(5)
	v_cndmask_b32_e64 v66, 1.0, v163, s[14:15]
	s_waitcnt lgkmcnt(4)
	v_cndmask_b32_e64 v74, 1.0, v96, s[16:17]
	v_mul_f32_e32 v66, v66, v74
	s_waitcnt lgkmcnt(3)
	v_cndmask_b32_e64 v74, 1.0, v166, s[18:19]
	v_mul_f32_e32 v99, v74, v66
	s_waitcnt lgkmcnt(2)
	v_cndmask_b32_e64 v66, 1.0, v173, s[16:17]
	s_waitcnt lgkmcnt(0)
	v_pk_mul_f32 v[172:173], v[172:173], v[174:175]
	v_mul_f32_e32 v176, v97, v163
	v_mov_b32_e32 v97, v172
	v_mov_b32_e32 v167, v173
	v_pk_mul_f32 v[96:97], v[96:97], v[166:167]
	v_mov_b32_e32 v177, v91
	v_pk_mul_f32 v[166:167], v[176:177], v[96:97]
	v_cndmask_b32_e64 v74, 1.0, v174, s[14:15]
	v_mov_b32_e32 v163, v166
	v_mov_b32_e32 v165, v167
	v_pk_mul_f32 v[96:97], v[162:163], v[164:165]
	v_mul_f32_e32 v66, v74, v66
	v_mov_b32_e32 v95, v97
	v_cndmask_b32_e64 v74, 1.0, v175, s[18:19]
	v_pk_mul_f32 v[92:93], v[92:93], v[94:95]
	v_mul_f32_e32 v171, v74, v66
	v_mul_f32_e32 v66, v72, v68
	v_mul_f32_e32 v68, v76, v70
	v_mul_f32_e32 v176, v101, v93
	v_mov_b32_e32 v101, v167
	v_mul_f32_e32 v95, v66, v93
	v_mul_f32_e32 v163, v68, v93
	v_mul_f32_e32 v165, v92, v93
	v_mul_f32_e32 v66, v169, v202
	v_mul_f32_e32 v68, v186, v201
	v_pk_mul_f32 v[92:93], v[98:99], v[100:101]
	v_mov_b32_e32 v169, v91
	v_min_f32_e32 v78, 0x42e6d4ca, v141
	v_mul_f32_e32 v99, v66, v93
	v_mul_f32_e32 v101, v68, v93
	v_mul_f32_e32 v186, v92, v93
	v_mul_f32_e32 v200, v200, v93
	v_pk_mul_f32 v[92:93], v[168:169], v[170:171]
	v_mul_f32_e32 v66, v204, v220
	v_mul_f32_e32 v204, v92, v93
	v_exp_f32_e32 v92, v78
	v_min_f32_e32 v98, 0x42e6d4ca, v140
	v_exp_f32_e32 v98, v98
	v_add_f32_e32 v94, 1.0, v92
	v_rcp_f32_e32 v94, v94
	v_cmp_lt_i32_e32 vcc, v180, v88
	v_mul_f32_e32 v68, v206, v219
	v_min_f32_e32 v162, 0x42e6d4ca, v138
	v_cndmask_b32_e32 v206, 0, v94, vcc
	v_mul_f32_e32 v92, v92, v94
	v_min_f32_e32 v94, 0x42e6d4ca, v139
	v_cndmask_b32_e32 v100, 1.0, v92, vcc
	v_add_f32_e32 v92, 1.0, v98
	v_rcp_f32_e32 v92, v92
	v_exp_f32_e32 v94, v94
	v_exp_f32_e32 v162, v162
	v_cmp_lt_i32_e32 vcc, v181, v88
	v_mul_f32_e32 v201, v66, v93
	v_min_f32_e32 v66, 0x42e6d4ca, v145
	v_cndmask_b32_e32 v219, 0, v92, vcc
	v_mul_f32_e32 v92, v98, v92
	v_add_f32_e32 v98, 1.0, v94
	v_rcp_f32_e32 v98, v98
	v_add_f32_e32 v166, 1.0, v162
	v_rcp_f32_e32 v166, v166
	v_cndmask_b32_e32 v164, 1.0, v92, vcc
	v_cmp_lt_i32_e32 vcc, v182, v88
	v_mul_f32_e32 v94, v94, v98
	s_nop 0
	v_cndmask_b32_e32 v92, 0, v98, vcc
	v_cndmask_b32_e32 v98, 1.0, v94, vcc
	v_mul_f32_e32 v94, v162, v166
	v_min_f32_e32 v162, 0x42e6d4ca, v137
	v_cmp_lt_i32_e32 vcc, v183, v88
	v_exp_f32_e32 v162, v162
	v_mul_f32_e32 v202, v68, v93
	v_cndmask_b32_e32 v94, 1.0, v94, vcc
	v_mul_f32_e32 v221, v94, v98
	v_mul_f32_e32 v222, v164, v221
	v_mul_f32_e32 v183, v100, v222
	v_add_f32_e32 v98, 1.0, v162
	v_min_f32_e32 v100, 0x42e6d4ca, v136
	v_rcp_f32_e32 v98, v98
	v_exp_f32_e32 v100, v100
	v_cndmask_b32_e32 v220, 0, v166, vcc
	v_cmp_lt_i32_e32 vcc, v184, v88
	v_min_f32_e32 v164, 0x42e6d4ca, v135
; __device__ __forceinline__ float fexp(float x) { return __builtin_amdgcn_exp2f(x * 1.44269504f); }
; __device__ __forceinline__ unsigned pack2(float a, float b) { unsigned r; asm volatile("v_cvt_pk_bf16_f32 %0, %1, %2" : "=v"(r) : "v"(a), "v"(b)); return r; }
; __device__ __forceinline__ void item_attn(const Params& p, int l, int aidx) {
;     ...
;             float f[4];
; #pragma unroll
;             for (int j = 0; j < 4; ++j) {
;               const float e = fexp(fminf(-z[m][n][j], 80.f));
;               const float sg = __builtin_amdgcn_rcpf(1.f + e);
;               if (decltype(MASKED)::value) {
;                 const bool ok = (kt * 64 + m * 16 + fq * 4 + j) < qpos;
;                 wgt[m][j] = ok ? sg : 0.f;
;                 f[j] = ok ? e * sg : 1.f;
;               } else { wgt[m][j] = sg; f[j] = e * sg; }
;             }
;             excl[m][3] = 1.f; excl[m][2] = f[3]; excl[m][1] = f[3] * f[2]; excl[m][0] = excl[m][1] * f[1];
;             const float G = excl[m][0] * f[0];
;             const float g1 = __shfl_xor(G, 16), g2 = __shfl_xor(G, 32), g3 = __shfl_xor(G, 48);
;             later[m] = ((fq ^ 1) > fq ? g1 : 1.f) * ((fq ^ 2) > fq ? g2 : 1.f) * ((fq ^ 3) > fq ? g3 : 1.f);
;             TT[m] = (G * g1) * (g2 * g3);
;           }
;           float lm[4]; lm[3] = carry[n]; lm[2] = lm[3] * TT[3]; lm[1] = lm[2] * TT[2]; lm[0] = lm[1] * TT[1];
; #pragma unroll
;           for (int m = 0; m < 4; ++m) {
;             const float base = later[m] * lm[m];
;             float pv[4];
; #pragma unroll
;             for (int j = 0; j < 4; ++j) pv[j] = wgt[m][j] * excl[m][j] * base;
;             pk[m][n][0] = pack2(pv[0], pv[1]); pk[m][n][1] = pack2(pv[2], pv[3]);
;           }
;           carry[n] = lm[0] * TT[0];
	s_nop 0
	v_cndmask_b32_e32 v184, 0, v98, vcc
	v_mul_f32_e32 v98, v162, v98
	v_cndmask_b32_e32 v162, 1.0, v98, vcc
	v_add_f32_e32 v98, 1.0, v100
	v_min_f32_e32 v166, 0x42e6d4ca, v134
	v_rcp_f32_e32 v98, v98
	v_exp_f32_e32 v164, v164
	v_exp_f32_e32 v166, v166
	v_cmp_lt_i32_e32 vcc, v185, v88
	v_min_f32_e32 v68, 0x42e6d4ca, v144
	v_exp_f32_e32 v66, v66
	v_cndmask_b32_e32 v185, 0, v98, vcc
	v_mul_f32_e32 v98, v100, v98
	v_add_f32_e32 v100, 1.0, v164
	v_rcp_f32_e32 v100, v100
	v_add_f32_e32 v168, 1.0, v166
	v_rcp_f32_e32 v168, v168
	v_cndmask_b32_e32 v167, 1.0, v98, vcc
	v_cmp_lt_i32_e32 vcc, v187, v88
	v_exp_f32_e32 v68, v68
	s_nop 0
	v_cndmask_b32_e32 v98, 0, v100, vcc
	v_mul_f32_e32 v100, v164, v100
	v_cndmask_b32_e32 v164, 1.0, v100, vcc
	v_mul_f32_e32 v100, v166, v168
	v_min_f32_e32 v166, 0x42e6d4ca, v132
	v_cmp_lt_i32_e32 vcc, v199, v88
	v_exp_f32_e32 v166, v166
	v_mul_f32_e32 v93, v64, v93
	v_cndmask_b32_e32 v100, 1.0, v100, vcc
	v_mul_f32_e32 v199, v100, v164
	v_mul_f32_e32 v223, v167, v199
	v_mul_f32_e32 v224, v162, v223
	v_add_f32_e32 v162, 1.0, v166
	v_min_f32_e32 v164, 0x42e6d4ca, v133
	v_rcp_f32_e32 v162, v162
	v_exp_f32_e32 v164, v164
	v_cndmask_b32_e32 v187, 0, v168, vcc
	v_cmp_lt_i32_e32 vcc, v203, v88
	v_add_f32_e32 v64, 1.0, v66
	v_min_f32_e32 v70, 0x42e6d4ca, v142
	v_cndmask_b32_e32 v203, 0, v162, vcc
	v_mul_f32_e32 v162, v166, v162
	v_min_f32_e32 v166, 0x42e6d4ca, v131
	v_cndmask_b32_e32 v167, 1.0, v162, vcc
	v_add_f32_e32 v162, 1.0, v164
	v_rcp_f32_e32 v72, v64
	v_add_f32_e32 v64, 1.0, v68
	v_rcp_f32_e32 v162, v162
	v_exp_f32_e32 v166, v166
	v_min_f32_e32 v168, 0x42e6d4ca, v130
	v_rcp_f32_e32 v74, v64
	v_min_f32_e32 v64, 0x42e6d4ca, v143
	v_exp_f32_e32 v70, v70
	v_exp_f32_e32 v168, v168
	v_exp_f32_e32 v64, v64
	v_cmp_lt_i32_e32 vcc, v205, v88
	v_add_f32_e32 v76, 1.0, v70
	v_add_f32_e32 v169, 1.0, v168
	v_cndmask_b32_e32 v205, 0, v162, vcc
	v_mul_f32_e32 v162, v164, v162
	v_add_f32_e32 v164, 1.0, v166
	v_rcp_f32_e32 v164, v164
	v_add_f32_e32 v79, 1.0, v71
	v_rcp_f32_e32 v78, v76
	v_add_f32_e32 v76, 1.0, v64
	v_rcp_f32_e32 v169, v169
	v_rcp_f32_e32 v79, v79
	v_rcp_f32_e32 v76, v76
	v_cndmask_b32_e32 v180, 1.0, v162, vcc
	v_cmp_lt_i32_e32 vcc, v207, v88
	v_pk_mul_f32 v[70:71], v[70:71], v[78:79]
	v_pk_mul_f32 v[64:65], v[64:65], v[76:77]
	v_cndmask_b32_e32 v162, 0, v164, vcc
	v_mul_f32_e32 v164, v166, v164
	v_cndmask_b32_e32 v166, 1.0, v164, vcc
	v_cmp_lt_i32_e32 vcc, v218, v88
	v_mul_f32_e32 v164, v168, v169
	v_or_b32_e32 v168, 3, v178
	v_cndmask_b32_e32 v207, 0, v169, vcc
	v_or_b32_e32 v169, 2, v178
	v_cndmask_b32_e32 v164, 1.0, v164, vcc
	v_cmp_lt_i32_e64 s[22:23], v169, v85
	v_cmp_lt_i32_e64 s[24:25], v168, v85
	v_mul_f32_e32 v218, v164, v166
	v_cmp_lt_i32_e64 s[20:21], v179, v85
	v_cndmask_b32_e64 v166, 0, v77, s[22:23]
	v_cndmask_b32_e64 v227, 0, v79, s[24:25]
	v_pk_mul_f32 v[68:69], v[68:69], v[74:75]
	v_cndmask_b32_e64 v71, 1.0, v71, s[24:25]
	v_cmp_lt_i32_e64 s[24:25], v169, v88
	v_cndmask_b32_e64 v169, 1.0, v65, s[22:23]
	v_cmp_lt_i32_e64 s[22:23], v168, v88
	v_cmp_lt_i32_e32 vcc, v178, v85
	v_cndmask_b32_e64 v226, 0, v75, s[20:21]
	v_pk_mul_f32 v[66:67], v[66:67], v[72:73]
	v_cndmask_b32_e64 v69, 1.0, v69, s[20:21]
	v_cmp_lt_i32_e64 s[20:21], v179, v88
	v_cndmask_b32_e64 v70, 1.0, v70, s[24:25]
	v_cndmask_b32_e64 v168, 1.0, v64, s[22:23]
	v_cndmask_b32_e32 v225, 0, v73, vcc
	v_cndmask_b32_e32 v67, 1.0, v67, vcc
	v_cmp_lt_i32_e32 vcc, v178, v88
	v_cndmask_b32_e64 v68, 1.0, v68, s[20:21]
	v_pk_mul_f32 v[170:171], v[70:71], v[168:169]
	v_cndmask_b32_e32 v66, 1.0, v66, vcc
	v_pk_mul_f32 v[172:173], v[68:69], v[170:171]
	v_mul_f32_e32 v228, v180, v218
	v_pk_mul_f32 v[174:175], v[66:67], v[172:173]
	ds_bpermute_b32 v177, v241, v175
	ds_bpermute_b32 v179, v242, v175
	ds_bpermute_b32 v181, v243, v175
	v_pk_mul_f32 v[96:97], v[96:97], v[96:97] op_sel:[0,1] op_sel_hi:[1,0]
	v_mul_f32_e32 v182, v167, v228
	s_waitcnt lgkmcnt(2)
	v_cndmask_b32_e64 v64, 1.0, v177, s[14:15]
	s_waitcnt lgkmcnt(1)
	v_cndmask_b32_e64 v65, 1.0, v179, s[16:17]
	v_mul_f32_e32 v64, v64, v65
	s_waitcnt lgkmcnt(0)
	v_cndmask_b32_e64 v65, 1.0, v181, s[18:19]
	v_mul_f32_e32 v167, v65, v64
	v_pk_mov_b32 v[64:65], v[70:71], v[96:97] op_sel:[1,0]
	v_mul_f32_e32 v66, v225, v173
	v_mul_f32_e32 v67, v226, v171
	v_pk_mul_f32 v[64:65], v[166:167], v[64:65]
	ds_bpermute_b32 v178, v242, v174
	v_mul_f32_e32 v66, v66, v65
	v_mul_f32_e32 v67, v67, v65
	v_mul_f32_e32 v64, v64, v65
	v_mul_f32_e32 v65, v227, v65
	v_cvt_pk_bf16_f32 v68, v66, v67
	v_cvt_pk_bf16_f32 v69, v64, v65
	v_cvt_pk_bf16_f32 v70, v95, v163
	v_cvt_pk_bf16_f32 v71, v165, v176
	ds_bpermute_b32 v176, v241, v174
	ds_bpermute_b32 v180, v243, v174
	ds_bpermute_b32 v75, v241, v183
	ds_bpermute_b32 v77, v242, v183
	ds_bpermute_b32 v79, v243, v183
	v_cndmask_b32_e64 v97, 0, v74, s[20:21]
	s_waitcnt lgkmcnt(4)
	v_cndmask_b32_e64 v73, 1.0, v176, s[14:15]
	v_cndmask_b32_e64 v74, 1.0, v178, s[16:17]
	v_mul_f32_e32 v73, v73, v74
	s_waitcnt lgkmcnt(3)
	v_cndmask_b32_e64 v74, 1.0, v180, s[18:19]
	v_cvt_pk_bf16_f32 v64, v99, v101
	v_cndmask_b32_e64 v101, 0, v76, s[22:23]
	v_mul_f32_e32 v73, v74, v73
	s_waitcnt lgkmcnt(2)
	v_cndmask_b32_e64 v74, 1.0, v75, s[14:15]
	s_waitcnt lgkmcnt(1)
	v_cndmask_b32_e64 v76, 1.0, v77, s[16:17]
	v_mul_f32_e32 v74, v74, v76
	s_waitcnt lgkmcnt(0)
	v_cndmask_b32_e64 v76, 1.0, v79, s[18:19]
	v_cvt_pk_bf16_f32 v65, v186, v200
	v_cvt_pk_bf16_f32 v66, v201, v202
	v_cvt_pk_bf16_f32 v67, v204, v93
	v_mul_f32_e32 v93, v76, v74
	ds_bpermute_b32 v163, v241, v224
	ds_bpermute_b32 v74, v242, v224
	v_cndmask_b32_e32 v95, 0, v72, vcc
	v_cndmask_b32_e64 v72, 0, v78, s[24:25]
	ds_bpermute_b32 v78, v243, v224
	v_pk_mul_f32 v[166:167], v[174:175], v[176:177]
	v_mul_f32_e32 v76, v183, v75
	ds_bpermute_b32 v183, v242, v182
	ds_bpermute_b32 v176, v241, v182
	ds_bpermute_b32 v177, v243, v182
	v_pk_mul_f32 v[174:175], v[178:179], v[180:181]
	s_waitcnt lgkmcnt(5)
; __device__ __forceinline__ float fexp(float x) { return __builtin_amdgcn_exp2f(x * 1.44269504f); }
; __device__ __forceinline__ unsigned pack2(float a, float b) { unsigned r; asm volatile("v_cvt_pk_bf16_f32 %0, %1, %2" : "=v"(r) : "v"(a), "v"(b)); return r; }
; __device__ __forceinline__ void item_attn(const Params& p, int l, int aidx) {
;     ...
;       auto sb_weights = [&](auto MASKED) {
; #pragma unroll
;         for (int n = 0; n < 2; ++n) {
;           const int qpos = qpos0 + 32 * wid + 16 * n + fr;
;           float wgt[4][4], excl[4][4], later[4], TT[4];
; #pragma unroll
;           for (int m = 0; m < 4; ++m) {
;             float f[4];
; #pragma unroll
;             for (int j = 0; j < 4; ++j) {
;               const float e = fexp(fminf(-z[m][n][j], 80.f));
;               const float sg = __builtin_amdgcn_rcpf(1.f + e);
;               if (decltype(MASKED)::value) {
;                 const bool ok = (kt * 64 + m * 16 + fq * 4 + j) < qpos;
;                 wgt[m][j] = ok ? sg : 0.f;
;                 f[j] = ok ? e * sg : 1.f;
;               } else { wgt[m][j] = sg; f[j] = e * sg; }
;             }
;             excl[m][3] = 1.f; excl[m][2] = f[3]; excl[m][1] = f[3] * f[2]; excl[m][0] = excl[m][1] * f[1];
;             const float G = excl[m][0] * f[0];
;             const float g1 = __shfl_xor(G, 16), g2 = __shfl_xor(G, 32), g3 = __shfl_xor(G, 48);
;             later[m] = ((fq ^ 1) > fq ? g1 : 1.f) * ((fq ^ 2) > fq ? g2 : 1.f) * ((fq ^ 3) > fq ? g3 : 1.f);
;             TT[m] = (G * g1) * (g2 * g3);
;           }
;           float lm[4]; lm[3] = carry[n]; lm[2] = lm[3] * TT[3]; lm[1] = lm[2] * TT[2]; lm[0] = lm[1] * TT[1];
; #pragma unroll
;           for (int m = 0; m < 4; ++m) {
;             const float base = later[m] * lm[m];
;             float pv[4];
; #pragma unroll
;             for (int j = 0; j < 4; ++j) pv[j] = wgt[m][j] * excl[m][j] * base;
;             pk[m][n][0] = pack2(pv[0], pv[1]); pk[m][n][1] = pack2(pv[2], pv[3]);
;           }
;           carry[n] = lm[0] * TT[0];
;         }
;       };
;       if (kt * 64 + 63 < qpos0 + 32 * wid) sb_weights(std::false_type{}); else sb_weights(std::true_type{});
	v_cndmask_b32_e64 v75, 1.0, v163, s[14:15]
	v_pk_mul_f32 v[166:167], v[166:167], v[174:175]
	v_mul_f32_e32 v174, v77, v79
	s_waitcnt lgkmcnt(4)
	v_cndmask_b32_e64 v77, 1.0, v74, s[16:17]
	v_mul_f32_e32 v75, v75, v77
	s_waitcnt lgkmcnt(3)
	v_cndmask_b32_e64 v77, 1.0, v78, s[18:19]
	v_mul_f32_e32 v99, v77, v75
	s_waitcnt lgkmcnt(2)
	v_cndmask_b32_e64 v75, 1.0, v183, s[16:17]
	s_waitcnt lgkmcnt(1)
	v_cndmask_b32_e64 v77, 1.0, v176, s[14:15]
	v_mul_f32_e32 v75, v77, v75
	s_waitcnt lgkmcnt(0)
	v_cndmask_b32_e64 v77, 1.0, v177, s[18:19]
	v_pk_mul_f32 v[176:177], v[182:183], v[176:177]
	v_mul_f32_e32 v165, v77, v75
	v_mov_b32_e32 v75, v176
	v_mov_b32_e32 v79, v177
	v_mul_f32_e32 v178, v224, v163
	v_pk_mul_f32 v[74:75], v[74:75], v[78:79]
	v_mov_b32_e32 v179, v90
	v_pk_mul_f32 v[78:79], v[178:179], v[74:75]
	v_mov_b32_e32 v163, v90
	v_mov_b32_e32 v77, v78
	v_mov_b32_e32 v175, v79
	v_pk_mul_f32 v[74:75], v[76:77], v[174:175]
	v_mul_f32_e32 v76, v97, v170
	v_pk_mul_f32 v[174:175], v[74:75], v[74:75] op_sel:[0,1] op_sel_hi:[1,0]
	v_mul_f32_e32 v74, v95, v172
	v_mov_b32_e32 v169, v174
	v_pk_mul_f32 v[72:73], v[72:73], v[168:169]
	v_mov_b32_e32 v95, v75
	v_mul_f32_e32 v74, v74, v73
	v_mul_f32_e32 v76, v76, v73
	v_mul_f32_e32 v77, v72, v73
	v_mul_f32_e32 v73, v101, v73
	v_cvt_pk_bf16_f32 v72, v74, v76
	v_cvt_pk_bf16_f32 v73, v77, v73
	v_mul_f32_e32 v76, v206, v222
	v_mul_f32_e32 v77, v219, v221
	v_pk_mul_f32 v[74:75], v[92:93], v[94:95]
	v_mov_b32_e32 v101, v79
	v_mul_f32_e32 v76, v76, v75
	v_mul_f32_e32 v77, v77, v75
	v_mul_f32_e32 v78, v74, v75
	v_mul_f32_e32 v75, v220, v75
	v_cvt_pk_bf16_f32 v74, v76, v77
	v_cvt_pk_bf16_f32 v75, v78, v75
	v_mul_f32_e32 v78, v184, v223
	v_mul_f32_e32 v92, v185, v199
	v_pk_mul_f32 v[76:77], v[98:99], v[100:101]
	v_mul_f32_e32 v93, v205, v218
	v_mul_f32_e32 v78, v78, v77
	v_mul_f32_e32 v79, v92, v77
	v_mul_f32_e32 v92, v76, v77
	v_mul_f32_e32 v77, v187, v77
	v_cvt_pk_bf16_f32 v76, v78, v79
	v_cvt_pk_bf16_f32 v77, v92, v77
	v_mul_f32_e32 v92, v203, v228
	v_pk_mul_f32 v[78:79], v[162:163], v[164:165]
	v_mov_b32_e32 v175, v96
	v_mul_f32_e32 v92, v92, v79
	v_mul_f32_e32 v93, v93, v79
	v_mul_f32_e32 v94, v78, v79
	v_mul_f32_e32 v79, v207, v79
	v_cvt_pk_bf16_f32 v78, v92, v93
	v_cvt_pk_bf16_f32 v79, v94, v79
	v_pk_mul_f32 v[92:93], v[166:167], v[174:175]
	s_mov_b64 s[0:1], 0
.LBB0_691:
	s_andn2_b64 vcc, exec, s[0:1]
	s_cbranch_vccnz .LBB0_693
	v_min_f32_e32 v64, 0x42e6d4ca, v160
	v_exp_f32_e32 v69, v64
	v_min_f32_e32 v64, 0x42e6d4ca, v161
	v_min_f32_e32 v66, 0x42e6d4ca, v158
	v_min_f32_e32 v65, 0x42e6d4ca, v159
	v_exp_f32_e32 v67, v64
	v_exp_f32_e32 v71, v66
	v_min_f32_e32 v66, 0x42e6d4ca, v157
	v_exp_f32_e32 v65, v65
	v_exp_f32_e32 v92, v66
	v_min_f32_e32 v66, 0x42e6d4ca, v156
	v_add_f32_e32 v64, 1.0, v69
	v_rcp_f32_e32 v77, v64
	v_add_f32_e32 v64, 1.0, v67
	v_exp_f32_e32 v66, v66
	v_rcp_f32_e32 v79, v64
	v_add_f32_e32 v64, 1.0, v65
	v_rcp_f32_e32 v73, v64
	v_add_f32_e32 v64, 1.0, v71
	v_min_f32_e32 v68, 0x42e6d4ca, v154
	v_rcp_f32_e32 v75, v64
	v_add_f32_e32 v64, 1.0, v92
	v_rcp_f32_e32 v94, v64
	v_add_f32_e32 v64, 1.0, v66
	v_exp_f32_e32 v97, v68
	v_min_f32_e32 v68, 0x42e6d4ca, v155
	v_rcp_f32_e32 v64, v64
	v_exp_f32_e32 v96, v68
	v_min_f32_e32 v68, 0x42e6d4ca, v151
	v_mul_f32_e32 v93, v66, v64
	v_add_f32_e32 v66, 1.0, v97
	v_rcp_f32_e32 v99, v66
	v_add_f32_e32 v66, 1.0, v96
	v_rcp_f32_e32 v98, v66
	v_min_f32_e32 v66, 0x42e6d4ca, v153
	v_exp_f32_e32 v66, v66
	v_min_f32_e32 v70, 0x42e6d4ca, v152
	v_exp_f32_e32 v100, v68
	v_add_f32_e32 v68, 1.0, v66
	v_rcp_f32_e32 v68, v68
	v_exp_f32_e32 v151, v70
	v_min_f32_e32 v72, 0x42e6d4ca, v148
	v_add_f32_e32 v70, 1.0, v100
	v_mul_f32_e32 v101, v66, v68
	v_add_f32_e32 v66, 1.0, v151
	v_rcp_f32_e32 v155, v66
	v_min_f32_e32 v66, 0x42e6d4ca, v150
	v_exp_f32_e32 v150, v66
	v_min_f32_e32 v66, 0x42e6d4ca, v149
	v_exp_f32_e32 v66, v66
	v_rcp_f32_e32 v152, v70
	v_min_f32_e32 v70, 0x42e6d4ca, v147
	v_exp_f32_e32 v147, v72
	v_min_f32_e32 v72, 0x42e6d4ca, v146
	v_exp_f32_e32 v146, v72
	v_exp_f32_e32 v156, v70
	v_add_f32_e32 v70, 1.0, v66
	v_rcp_f32_e32 v70, v70
	v_add_f32_e32 v72, 1.0, v147
	v_rcp_f32_e32 v149, v72
	v_add_f32_e32 v72, 1.0, v146
	v_rcp_f32_e32 v148, v72
	v_mul_f32_e32 v157, v66, v70
	v_add_f32_e32 v66, 1.0, v150
	v_add_f32_e32 v72, 1.0, v156
	v_rcp_f32_e32 v154, v66
	v_rcp_f32_e32 v158, v72
	v_pk_mul_f32 v[146:147], v[146:147], v[148:149]
	v_pk_mul_f32 v[96:97], v[96:97], v[98:99]
	v_pk_mul_f32 v[160:161], v[146:147], v[146:147] op_sel:[0,1] op_sel_hi:[1,0]
	v_pk_mul_f32 v[150:151], v[150:151], v[154:155]
	v_mov_b32_e32 v159, v160
	v_pk_mul_f32 v[156:157], v[156:157], v[158:159]
	v_pk_mul_f32 v[166:167], v[150:151], v[150:151] op_sel:[0,1] op_sel_hi:[1,0]
	v_pk_mul_f32 v[162:163], v[156:157], v[156:157] op_sel:[0,1] op_sel_hi:[1,0]
	v_mov_b32_e32 v153, v166
	ds_bpermute_b32 v163, v242, v162
	ds_bpermute_b32 v164, v241, v162
	ds_bpermute_b32 v165, v243, v162
	v_pk_mul_f32 v[100:101], v[100:101], v[152:153]
	v_mul_f32_e32 v68, v68, v166
	v_mul_f32_e32 v74, v100, v101
	ds_bpermute_b32 v76, v241, v74
	ds_bpermute_b32 v168, v242, v74
	ds_bpermute_b32 v170, v243, v74
	s_waitcnt lgkmcnt(5)
	v_cndmask_b32_e64 v66, 1.0, v163, s[16:17]
	s_waitcnt lgkmcnt(3)
	v_pk_mul_f32 v[162:163], v[162:163], v[164:165]
	v_cndmask_b32_e64 v72, 1.0, v164, s[14:15]
	v_mov_b32_e32 v169, v162
	v_mov_b32_e32 v171, v163
	v_mul_f32_e32 v66, v72, v66
	v_cndmask_b32_e64 v72, 1.0, v165, s[18:19]
	s_waitcnt lgkmcnt(2)
	v_mul_f32_e32 v164, v74, v76
	s_waitcnt lgkmcnt(0)
; __device__ __forceinline__ float fexp(float x) { return __builtin_amdgcn_exp2f(x * 1.44269504f); }
; __device__ __forceinline__ unsigned pack2(float a, float b) { unsigned r; asm volatile("v_cvt_pk_bf16_f32 %0, %1, %2" : "=v"(r) : "v"(a), "v"(b)); return r; }
; __device__ __forceinline__ void item_attn(const Params& p, int l, int aidx) {
;     ...
; #pragma unroll
;           for (int m = 0; m < 4; ++m) {
;             float f[4];
; #pragma unroll
;             for (int j = 0; j < 4; ++j) {
;               const float e = fexp(fminf(-z[m][n][j], 80.f));
;               const float sg = __builtin_amdgcn_rcpf(1.f + e);
;               if (decltype(MASKED)::value) {
;                 const bool ok = (kt * 64 + m * 16 + fq * 4 + j) < qpos;
;                 wgt[m][j] = ok ? sg : 0.f;
;                 f[j] = ok ? e * sg : 1.f;
;               } else { wgt[m][j] = sg; f[j] = e * sg; }
;             }
;             excl[m][3] = 1.f; excl[m][2] = f[3]; excl[m][1] = f[3] * f[2]; excl[m][0] = excl[m][1] * f[1];
;             const float G = excl[m][0] * f[0];
;             const float g1 = __shfl_xor(G, 16), g2 = __shfl_xor(G, 32), g3 = __shfl_xor(G, 48);
;             later[m] = ((fq ^ 1) > fq ? g1 : 1.f) * ((fq ^ 2) > fq ? g2 : 1.f) * ((fq ^ 3) > fq ? g3 : 1.f);
;             TT[m] = (G * g1) * (g2 * g3);
;           }
;           float lm[4]; lm[3] = carry[n]; lm[2] = lm[3] * TT[3]; lm[1] = lm[2] * TT[2]; lm[0] = lm[1] * TT[1];
; #pragma unroll
;           for (int m = 0; m < 4; ++m) {
;             const float base = later[m] * lm[m];
;             float pv[4];
; #pragma unroll
;             for (int j = 0; j < 4; ++j) pv[j] = wgt[m][j] * excl[m][j] * base;
;             pk[m][n][0] = pack2(pv[0], pv[1]); pk[m][n][1] = pack2(pv[2], pv[3]);
;           }
;           carry[n] = lm[0] * TT[0];
	v_pk_mul_f32 v[162:163], v[168:169], v[170:171]
	v_mov_b32_e32 v165, v91
	v_pk_mul_f32 v[162:163], v[164:165], v[162:163]
	v_pk_mul_f32 v[164:165], v[96:97], v[96:97] op_sel:[0,1] op_sel_hi:[1,0]
	v_mul_f32_e32 v147, v72, v66
	v_cndmask_b32_e64 v66, 1.0, v76, s[14:15]
	v_cndmask_b32_e64 v72, 1.0, v168, s[16:17]
	v_mov_b32_e32 v95, v164
	v_mul_f32_e32 v66, v66, v72
	v_cndmask_b32_e64 v72, 1.0, v170, s[18:19]
	v_pk_mul_f32 v[92:93], v[92:93], v[94:95]
	v_mul_f32_e32 v151, v72, v66
	v_mul_f32_e32 v66, v92, v93
	ds_bpermute_b32 v72, v241, v66
	ds_bpermute_b32 v74, v242, v66
	ds_bpermute_b32 v78, v243, v66
	v_mul_f32_e32 v76, v152, v101
	v_mov_b32_e32 v101, v162
	s_waitcnt lgkmcnt(2)
	v_cndmask_b32_e64 v92, 1.0, v72, s[14:15]
	s_waitcnt lgkmcnt(1)
	v_cndmask_b32_e64 v95, 1.0, v74, s[16:17]
	v_mul_f32_e32 v100, v66, v72
	s_waitcnt lgkmcnt(0)
	v_mul_f32_e32 v152, v74, v78
	v_mov_b32_e32 v153, v163
	v_mul_f32_e32 v92, v92, v95
	v_cndmask_b32_e64 v95, 1.0, v78, s[18:19]
	v_pk_mul_f32 v[100:101], v[100:101], v[152:153]
	v_mul_f32_e32 v97, v95, v92
	v_mul_f32_e32 v66, v94, v93
	v_mov_b32_e32 v92, v99
	v_mov_b32_e32 v93, v101
	v_mul_f32_e32 v64, v64, v164
	v_pk_mul_f32 v[92:93], v[92:93], v[96:97]
	v_mov_b32_e32 v162, v155
	v_mul_f32_e32 v97, v66, v93
	v_mul_f32_e32 v156, v64, v93
	v_mul_f32_e32 v161, v92, v93
	v_mul_f32_e32 v164, v98, v93
	v_pk_mul_f32 v[92:93], v[162:163], v[150:151]
	v_mul_f32_e32 v64, v158, v157
	v_mul_f32_e32 v162, v76, v93
	v_mul_f32_e32 v163, v68, v93
	v_mul_f32_e32 v165, v92, v93
	v_mul_f32_e32 v166, v154, v93
	v_mov_b32_e32 v92, v149
	v_mov_b32_e32 v93, v91
	v_pk_mul_f32 v[92:93], v[92:93], v[146:147]
	v_min_f32_e32 v137, 0x42e6d4ca, v137
	v_mul_f32_e32 v167, v64, v93
	v_mul_f32_e32 v64, v70, v160
	v_mul_f32_e32 v160, v64, v93
	v_min_f32_e32 v64, 0x42e6d4ca, v145
	v_exp_f32_e32 v68, v64
	v_min_f32_e32 v64, 0x42e6d4ca, v144
	v_mul_f32_e32 v168, v92, v93
	v_min_f32_e32 v92, 0x42e6d4ca, v141
	v_exp_f32_e32 v66, v64
	v_add_f32_e32 v64, 1.0, v68
	v_rcp_f32_e32 v76, v64
	v_min_f32_e32 v64, 0x42e6d4ca, v142
	v_exp_f32_e32 v94, v92
	v_min_f32_e32 v92, 0x42e6d4ca, v140
	v_exp_f32_e32 v70, v64
	v_min_f32_e32 v64, 0x42e6d4ca, v143
	v_exp_f32_e32 v92, v92
	v_exp_f32_e32 v64, v64
	v_mul_f32_e32 v169, v148, v93
	v_add_f32_e32 v93, 1.0, v94
	v_add_f32_e32 v72, 1.0, v66
	v_rcp_f32_e32 v96, v93
	v_add_f32_e32 v93, 1.0, v92
	v_rcp_f32_e32 v78, v72
	v_add_f32_e32 v72, 1.0, v70
	v_rcp_f32_e32 v170, v93
	v_min_f32_e32 v93, 0x42e6d4ca, v139
	v_min_f32_e32 v136, 0x42e6d4ca, v136
	v_rcp_f32_e32 v74, v72
	v_add_f32_e32 v72, 1.0, v64
	v_rcp_f32_e32 v72, v72
	v_exp_f32_e32 v99, v93
	v_min_f32_e32 v93, 0x42e6d4ca, v138
	v_exp_f32_e32 v138, v137
	v_exp_f32_e32 v137, v136
	v_min_f32_e32 v135, 0x42e6d4ca, v135
	v_min_f32_e32 v134, 0x42e6d4ca, v134
	v_add_f32_e32 v139, 1.0, v137
	v_pk_mul_f32 v[70:71], v[70:71], v[74:75]
	v_pk_mul_f32 v[146:147], v[64:65], v[72:73]
	v_rcp_f32_e32 v171, v139
	v_exp_f32_e32 v135, v135
	v_min_f32_e32 v133, 0x42e6d4ca, v133
	v_pk_mul_f32 v[66:67], v[66:67], v[78:79]
	v_pk_mul_f32 v[148:149], v[70:71], v[146:147]
	v_exp_f32_e32 v134, v134
	v_min_f32_e32 v132, 0x42e6d4ca, v132
	v_min_f32_e32 v130, 0x42e6d4ca, v130
	v_pk_mul_f32 v[68:69], v[68:69], v[76:77]
	v_pk_mul_f32 v[150:151], v[66:67], v[148:149]
	v_exp_f32_e32 v133, v133
	v_min_f32_e32 v131, 0x42e6d4ca, v131
	v_pk_mul_f32 v[152:153], v[68:69], v[150:151]
	v_exp_f32_e32 v132, v132
	v_exp_f32_e32 v130, v130
	ds_bpermute_b32 v155, v241, v153
	ds_bpermute_b32 v157, v242, v153
	v_mul_f32_e32 v139, v137, v171
	v_add_f32_e32 v137, 1.0, v135
	v_exp_f32_e32 v131, v131
	ds_bpermute_b32 v159, v243, v153
	v_rcp_f32_e32 v141, v137
	v_add_f32_e32 v137, 1.0, v134
	v_rcp_f32_e32 v140, v137
	v_add_f32_e32 v137, 1.0, v133
	v_rcp_f32_e32 v172, v137
	v_add_f32_e32 v137, 1.0, v132
	v_add_f32_e32 v64, 1.0, v130
	v_rcp_f32_e32 v142, v137
	v_add_f32_e32 v137, 1.0, v131
	v_rcp_f32_e32 v144, v64
	s_waitcnt lgkmcnt(2)
	v_cndmask_b32_e64 v64, 1.0, v155, s[14:15]
	s_waitcnt lgkmcnt(1)
	v_cndmask_b32_e64 v65, 1.0, v157, s[16:17]
	v_rcp_f32_e32 v145, v137
	v_mul_f32_e32 v64, v64, v65
	s_waitcnt lgkmcnt(0)
	v_cndmask_b32_e64 v65, 1.0, v159, s[18:19]
	v_pk_mul_f32 v[100:101], v[100:101], v[100:101] op_sel:[0,1] op_sel_hi:[1,0]
	ds_bpermute_b32 v154, v241, v152
	v_mul_f32_e32 v65, v65, v64
	v_mov_b32_e32 v64, v73
	v_pk_mov_b32 v[66:67], v[70:71], v[100:101] op_sel:[1,0]
	v_mul_f32_e32 v68, v77, v151
	v_mul_f32_e32 v69, v79, v149
	v_pk_mul_f32 v[64:65], v[64:65], v[66:67]
	ds_bpermute_b32 v158, v243, v152
	v_mul_f32_e32 v66, v68, v65
	v_mul_f32_e32 v67, v69, v65
	v_mul_f32_e32 v64, v64, v65
	v_mul_f32_e32 v65, v75, v65
	v_cvt_pk_bf16_f32 v68, v66, v67
	v_cvt_pk_bf16_f32 v69, v64, v65
	v_cvt_pk_bf16_f32 v70, v97, v156
	ds_bpermute_b32 v156, v242, v152
	v_pk_mul_f32 v[130:131], v[130:131], v[144:145]
	s_waitcnt lgkmcnt(2)
; __device__ __forceinline__ float fexp(float x) { return __builtin_amdgcn_exp2f(x * 1.44269504f); }
; __device__ __forceinline__ unsigned pack2(float a, float b) { unsigned r; asm volatile("v_cvt_pk_bf16_f32 %0, %1, %2" : "=v"(r) : "v"(a), "v"(b)); return r; }
; __device__ __forceinline__ void item_attn(const Params& p, int l, int aidx) {
;     ...
; #pragma unroll
;           for (int m = 0; m < 4; ++m) {
;             float f[4];
; #pragma unroll
;             for (int j = 0; j < 4; ++j) {
;               const float e = fexp(fminf(-z[m][n][j], 80.f));
;               const float sg = __builtin_amdgcn_rcpf(1.f + e);
;               if (decltype(MASKED)::value) {
;                 const bool ok = (kt * 64 + m * 16 + fq * 4 + j) < qpos;
;                 wgt[m][j] = ok ? sg : 0.f;
;                 f[j] = ok ? e * sg : 1.f;
;               } else { wgt[m][j] = sg; f[j] = e * sg; }
;             }
;             excl[m][3] = 1.f; excl[m][2] = f[3]; excl[m][1] = f[3] * f[2]; excl[m][0] = excl[m][1] * f[1];
;             const float G = excl[m][0] * f[0];
;             const float g1 = __shfl_xor(G, 16), g2 = __shfl_xor(G, 32), g3 = __shfl_xor(G, 48);
;             later[m] = ((fq ^ 1) > fq ? g1 : 1.f) * ((fq ^ 2) > fq ? g2 : 1.f) * ((fq ^ 3) > fq ? g3 : 1.f);
;             TT[m] = (G * g1) * (g2 * g3);
;           }
;           float lm[4]; lm[3] = carry[n]; lm[2] = lm[3] * TT[3]; lm[1] = lm[2] * TT[2]; lm[0] = lm[1] * TT[1];
; #pragma unroll
;           for (int m = 0; m < 4; ++m) {
;             const float base = later[m] * lm[m];
;             float pv[4];
; #pragma unroll
;             for (int j = 0; j < 4; ++j) pv[j] = wgt[m][j] * excl[m][j] * base;
;             pk[m][n][0] = pack2(pv[0], pv[1]); pk[m][n][1] = pack2(pv[2], pv[3]);
;           }
;           carry[n] = lm[0] * TT[0];
	v_pk_mul_f32 v[152:153], v[152:153], v[154:155]
	v_cndmask_b32_e64 v73, 1.0, v154, s[14:15]
	v_pk_mul_f32 v[154:155], v[130:131], v[130:131] op_sel:[0,1] op_sel_hi:[1,0]
	v_mul_f32_e32 v133, v133, v172
	v_mov_b32_e32 v143, v154
	v_pk_mul_f32 v[132:133], v[132:133], v[142:143]
	v_cvt_pk_bf16_f32 v71, v161, v164
	v_cvt_pk_bf16_f32 v64, v162, v163
	v_cvt_pk_bf16_f32 v65, v165, v166
	v_cvt_pk_bf16_f32 v66, v167, v160
	s_waitcnt lgkmcnt(0)
	v_pk_mul_f32 v[160:161], v[156:157], v[158:159]
	v_cndmask_b32_e64 v75, 1.0, v156, s[16:17]
	v_pk_mul_f32 v[156:157], v[132:133], v[132:133] op_sel:[0,1] op_sel_hi:[1,0]
	v_mul_f32_e32 v73, v73, v75
	v_cndmask_b32_e64 v75, 1.0, v158, s[18:19]
	ds_bpermute_b32 v157, v242, v156
	ds_bpermute_b32 v158, v241, v156
	v_add_f32_e32 v136, 1.0, v138
	v_rcp_f32_e32 v136, v136
	v_mul_f32_e32 v75, v75, v73
	v_mul_f32_e32 v73, v76, v150
	s_waitcnt lgkmcnt(1)
	v_cndmask_b32_e64 v76, 1.0, v157, s[16:17]
	s_waitcnt lgkmcnt(0)
	v_cndmask_b32_e64 v77, 1.0, v158, s[14:15]
	v_mul_f32_e32 v97, v77, v76
	v_pk_mul_f32 v[76:77], v[134:135], v[140:141]
	v_exp_f32_e32 v98, v93
	v_mul_f32_e32 v101, v78, v148
	v_pk_mul_f32 v[78:79], v[76:77], v[76:77] op_sel:[0,1] op_sel_hi:[1,0]
	v_mul_f32_e32 v95, v92, v170
	v_mov_b32_e32 v137, v78
	v_pk_mul_f32 v[134:135], v[138:139], v[136:137]
	v_add_f32_e32 v92, 1.0, v99
	ds_bpermute_b32 v159, v243, v156
	v_mul_f32_e32 v79, v134, v135
	v_rcp_f32_e32 v93, v92
	v_add_f32_e32 v92, 1.0, v98
	ds_bpermute_b32 v132, v241, v79
	ds_bpermute_b32 v138, v242, v79
	v_rcp_f32_e32 v92, v92
	ds_bpermute_b32 v148, v243, v79
	s_waitcnt lgkmcnt(3)
	v_cndmask_b32_e64 v131, 1.0, v159, s[18:19]
	v_pk_mul_f32 v[150:151], v[156:157], v[158:159]
	v_mul_f32_e32 v131, v131, v97
	s_waitcnt lgkmcnt(2)
	v_cndmask_b32_e64 v77, 1.0, v132, s[14:15]
	s_waitcnt lgkmcnt(1)
	v_cndmask_b32_e64 v97, 1.0, v138, s[16:17]
	v_mov_b32_e32 v139, v150
	v_mov_b32_e32 v149, v151
	v_pk_mul_f32 v[98:99], v[98:99], v[92:93]
	v_mul_f32_e32 v77, v77, v97
	s_waitcnt lgkmcnt(0)
	v_cndmask_b32_e64 v97, 1.0, v148, s[18:19]
	v_pk_mul_f32 v[138:139], v[138:139], v[148:149]
	v_pk_mul_f32 v[148:149], v[98:99], v[98:99] op_sel:[0,1] op_sel_hi:[1,0]
	v_mul_f32_e32 v77, v97, v77
	v_mov_b32_e32 v97, v148
	v_pk_mul_f32 v[94:95], v[94:95], v[96:97]
	v_mul_f32_e32 v156, v79, v132
	v_mul_f32_e32 v79, v94, v95
	ds_bpermute_b32 v94, v241, v79
	ds_bpermute_b32 v97, v242, v79
	ds_bpermute_b32 v128, v243, v79
	v_mov_b32_e32 v157, v90
	v_mul_f32_e32 v132, v171, v78
	s_waitcnt lgkmcnt(2)
	v_cndmask_b32_e64 v78, 1.0, v94, s[14:15]
	s_waitcnt lgkmcnt(1)
	v_cndmask_b32_e64 v99, 1.0, v97, s[16:17]
	v_pk_mul_f32 v[138:139], v[156:157], v[138:139]
	v_mul_f32_e32 v78, v78, v99
	s_waitcnt lgkmcnt(0)
	v_cndmask_b32_e64 v99, 1.0, v128, s[18:19]
	v_mul_f32_e32 v99, v99, v78
	v_mul_f32_e32 v78, v79, v94
	v_mul_f32_e32 v128, v97, v128
	v_mov_b32_e32 v79, v138
	v_mov_b32_e32 v129, v139
	v_pk_mul_f32 v[78:79], v[78:79], v[128:129]
	v_mul_f32_e32 v96, v96, v95
	v_pk_mul_f32 v[94:95], v[78:79], v[78:79] op_sel:[0,1] op_sel_hi:[1,0]
	v_cvt_pk_bf16_f32 v67, v168, v169
	v_mul_f32_e32 v97, v170, v148
	v_mov_b32_e32 v147, v94
	v_pk_mul_f32 v[74:75], v[74:75], v[146:147]
	v_mov_b32_e32 v138, v141
	v_mul_f32_e32 v78, v101, v75
	v_mul_f32_e32 v73, v73, v75
	v_mul_f32_e32 v74, v74, v75
	v_mul_f32_e32 v75, v72, v75
	v_cvt_pk_bf16_f32 v72, v73, v78
	v_mov_b32_e32 v78, v93
	v_cvt_pk_bf16_f32 v73, v74, v75
	v_pk_mul_f32 v[74:75], v[78:79], v[98:99]
	v_mul_f32_e32 v127, v136, v135
	v_mul_f32_e32 v78, v96, v75
	v_mul_f32_e32 v79, v97, v75
	v_pk_mul_f32 v[76:77], v[138:139], v[76:77]
	v_mul_f32_e32 v93, v74, v75
	v_mul_f32_e32 v75, v92, v75
	v_cvt_pk_bf16_f32 v74, v78, v79
	v_mul_f32_e32 v78, v127, v77
	v_mul_f32_e32 v79, v132, v77
	v_cvt_pk_bf16_f32 v75, v93, v75
	v_mul_f32_e32 v92, v76, v77
	v_mul_f32_e32 v77, v140, v77
	v_cvt_pk_bf16_f32 v76, v78, v79
	v_pk_mov_b32 v[78:79], v[144:145], v[90:91] op_sel:[1,0]
	v_cvt_pk_bf16_f32 v77, v92, v77
	v_mul_f32_e32 v92, v142, v133
	v_pk_mul_f32 v[78:79], v[78:79], v[130:131]
	v_mul_f32_e32 v91, v172, v154
	v_pk_mul_f32 v[152:153], v[152:153], v[160:161]
	v_mul_f32_e32 v90, v92, v79
	v_mul_f32_e32 v91, v91, v79
	v_mul_f32_e32 v92, v78, v79
	v_mul_f32_e32 v79, v144, v79
	v_mov_b32_e32 v95, v100
	v_cvt_pk_bf16_f32 v78, v90, v91
	v_cvt_pk_bf16_f32 v79, v92, v79
	v_pk_mul_f32 v[92:93], v[152:153], v[94:95]

; __device__ __forceinline__ float fexp(float x) { return __builtin_amdgcn_exp2f(x * 1.44269504f); }
; __device__ __forceinline__ void item_attn(const Params& p, int l, int aidx) {
;     ...
;     if (!wave_done && kt * 64 < wave_qmax) {
;       f32x4 z[4][2];
; #pragma unroll
;       for (int m = 0; m < 4; ++m) {
;         bf16x8 a0 = *reinterpret_cast<const bf16x8*>(Ks + (m * 16 + fr) * 72 + fq * 8);
;         bf16x8 a1 = *reinterpret_cast<const bf16x8*>(Ks + (m * 16 + fr) * 72 + 32 + fq * 8);
; #pragma unroll
;         for (int n = 0; n < 2; ++n) {
;           f32x4 zz = f32x4{0.f, 0.f, 0.f, 0.f};
;           zz = __builtin_amdgcn_mfma_f32_16x16x32_bf16(a0, qf[n][0], zz, 0, 0, 0);
;           zz = __builtin_amdgcn_mfma_f32_16x16x32_bf16(a1, qf[n][1], zz, 0, 0, 0);
;           z[m][n] = zz;
;         }
;       }
;       unsigned pk[4][2][2];
;       auto sb_weights = [&](auto MASKED) {
; #pragma unroll
;         for (int n = 0; n < 2; ++n) {
;           const int qpos = qpos0 + 32 * wid + 16 * n + fr;
;           float wgt[4][4], excl[4][4], later[4], TT[4];
; #pragma unroll
;           for (int m = 0; m < 4; ++m) {
;             float f[4];
; #pragma unroll
;             for (int j = 0; j < 4; ++j) {
;               const float e = fexp(fminf(-z[m][n][j], 80.f));
;               const float sg = __builtin_amdgcn_rcpf(1.f + e);
;               if (decltype(MASKED)::value) {
;                 const bool ok = (kt * 64 + m * 16 + fq * 4 + j) < qpos;
;                 wgt[m][j] = ok ? sg : 0.f;
;                 f[j] = ok ? e * sg : 1.f;
;               } else { wgt[m][j] = sg; f[j] = e * sg; }
;             }
;             excl[m][3] = 1.f; excl[m][2] = f[3]; excl[m][1] = f[3] * f[2]; excl[m][0] = excl[m][1] * f[1];
;             const float G = excl[m][0] * f[0];
;             const float g1 = __shfl_xor(G, 16), g2 = __shfl_xor(G, 32), g3 = __shfl_xor(G, 48);
;             later[m] = ((fq ^ 1) > fq ? g1 : 1.f) * ((fq ^ 2) > fq ? g2 : 1.f) * ((fq ^ 3) > fq ? g3 : 1.f);
;             TT[m] = (G * g1) * (g2 * g3);
.LBB0_760:
	s_andn2_b64 vcc, exec, s[4:5]
	s_mov_b64 s[0:1], -1
	s_cbranch_vccnz .LBB0_767
	s_cmp_ge_i32 s49, s51
	s_mov_b64 s[0:1], 0
	s_cbranch_scc1 .LBB0_767
	ds_read_b128 v[64:67], v118
	ds_read_b128 v[68:71], v118 offset:64
	s_mov_b32 s100, 0xbfb8aa3b
	s_nop 0
	s_nop 0
	s_waitcnt lgkmcnt(1)
	v_mfma_f32_16x16x32_bf16 v[72:75], v[64:67], v[4:7], 0
	s_nop 0
	s_add_i32 s0, s49, 63
	s_cmp_lt_i32 s0, s50
	v_mfma_f32_16x16x32_bf16 v[64:67], v[64:67], v[12:15], 0
	s_nop 0
	s_nop 0
	s_nop 0
	s_waitcnt lgkmcnt(0)
	v_mfma_f32_16x16x32_bf16 v[72:75], v[68:71], v[0:3], v[72:75]
	s_nop 0
	s_mov_b64 s[0:1], -1
	v_mfma_f32_16x16x32_bf16 v[64:67], v[68:71], v[8:11], v[64:67]
	ds_read_b128 v[68:71], v118 offset:2304
	ds_read_b128 v[76:79], v118 offset:2368
	s_nop 0
	s_nop 1
	s_nop 0
	s_waitcnt lgkmcnt(1)
	v_mfma_f32_16x16x32_bf16 v[92:95], v[68:71], v[4:7], 0
	v_pk_mul_f32 v[160:161], v[72:73], s[100:101] op_sel_hi:[1,0]
	s_nop 0
	v_pk_mul_f32 v[158:159], v[74:75], s[100:101] op_sel:[1,0] op_sel_hi:[0,0]
	v_mfma_f32_16x16x32_bf16 v[68:71], v[68:71], v[12:15], 0
	s_nop 0
	v_pk_mul_f32 v[144:145], v[64:65], s[100:101] op_sel:[1,0] op_sel_hi:[0,0]
	s_nop 0
	s_waitcnt lgkmcnt(0)
	v_mfma_f32_16x16x32_bf16 v[92:95], v[76:79], v[0:3], v[92:95]
	v_pk_mul_f32 v[142:143], v[66:67], s[100:101] op_sel_hi:[1,0]
	v_mfma_f32_16x16x32_bf16 v[68:71], v[76:79], v[8:11], v[68:71]
	ds_read_b128 v[76:79], v118 offset:4608
	ds_read_b128 v[96:99], v118 offset:4672
	s_nop 3
	s_nop 0
	v_pk_mul_f32 v[156:157], v[92:93], s[100:101] op_sel:[1,0] op_sel_hi:[0,0]
	s_waitcnt lgkmcnt(1)
	v_mfma_f32_16x16x32_bf16 v[128:131], v[76:79], v[4:7], 0
	s_nop 0
	v_pk_mul_f32 v[154:155], v[94:95], s[100:101] op_sel_hi:[1,0]
	v_mfma_f32_16x16x32_bf16 v[76:79], v[76:79], v[12:15], 0
	s_waitcnt lgkmcnt(0)
	v_mfma_f32_16x16x32_bf16 v[130:133], v[96:99], v[0:3], v[128:131]
	v_mfma_f32_16x16x32_bf16 v[76:79], v[96:99], v[8:11], v[76:79]
	ds_read_b128 v[96:99], v118 offset:6912
	ds_read_b128 v[134:137], v118 offset:6976
	s_nop 0
	s_nop 0
	s_waitcnt lgkmcnt(1)
	v_mfma_f32_16x16x32_bf16 v[138:141], v[96:99], v[4:7], 0
	s_nop 0
	v_mul_f32_e32 v151, s100, v130
	v_mul_f32_e32 v153, s100, v131
	v_mfma_f32_16x16x32_bf16 v[96:99], v[96:99], v[12:15], 0
	s_nop 0
	s_nop 0
	v_mul_f32_e32 v152, s100, v132
	s_waitcnt lgkmcnt(0)
	v_mfma_f32_16x16x32_bf16 v[138:141], v[134:137], v[0:3], v[138:141]
	v_mul_f32_e32 v150, s100, v133
	v_mfma_f32_16x16x32_bf16 v[96:99], v[134:137], v[8:11], v[96:99]
	s_nop 0
	s_nop 4
	v_mul_f32_e32 v147, s100, v138
	v_mul_f32_e32 v149, s100, v139
	v_mul_f32_e32 v148, s100, v140
	v_mul_f32_e32 v146, s100, v141
	s_nop 0
	v_pk_mul_f32 v[140:141], v[68:69], s[100:101] op_sel:[1,0] op_sel_hi:[0,0]
	s_nop 0
	v_pk_mul_f32 v[138:139], v[70:71], s[100:101] op_sel:[1,0] op_sel_hi:[0,0]
	v_pk_mul_f32 v[136:137], v[76:77], s[100:101] op_sel:[1,0] op_sel_hi:[0,0]
	s_nop 0
	v_pk_mul_f32 v[134:135], v[78:79], s[100:101] op_sel:[1,0] op_sel_hi:[0,0]
	s_nop 0
	v_pk_mul_f32 v[132:133], v[96:97], s[100:101] op_sel_hi:[1,0]
	s_nop 0
	v_pk_mul_f32 v[130:131], v[98:99], s[100:101] op_sel:[1,0] op_sel_hi:[0,0]
	s_cbranch_scc1 .LBB0_764
	v_min_f32_e32 v64, 0x42e6d4ca, v160
	v_exp_f32_e32 v69, v64
	v_min_f32_e32 v64, 0x42e6d4ca, v161
	v_exp_f32_e32 v67, v64
	v_min_f32_e32 v64, 0x42e6d4ca, v159
	v_add_f32_e32 v65, 1.0, v69
	v_rcp_f32_e32 v73, v65
	v_exp_f32_e32 v65, v64
	v_min_f32_e32 v66, 0x42e6d4ca, v157
	v_add_f32_e32 v64, 1.0, v67
	v_exp_f32_e32 v66, v66
	v_rcp_f32_e32 v75, v64
	v_add_f32_e32 v64, 1.0, v65
	v_rcp_f32_e32 v77, v64
	v_min_f32_e32 v64, 0x42e6d4ca, v158
	v_min_f32_e32 v68, 0x42e6d4ca, v156
	v_exp_f32_e32 v71, v64
	v_add_f32_e32 v64, 1.0, v66
	v_rcp_f32_e32 v64, v64
	v_exp_f32_e32 v68, v68
	v_add_u32_e32 v178, s49, v114
	v_add_u32_e32 v180, 16, v178
	v_cmp_lt_i32_e32 vcc, v180, v85
	v_min_f32_e32 v72, 0x42e6d4ca, v154
	s_nop 0
	v_cndmask_b32_e32 v70, 0, v64, vcc
	v_mul_f32_e32 v64, v66, v64
	v_add_f32_e32 v66, 1.0, v68
	v_rcp_f32_e32 v66, v66
	v_exp_f32_e32 v72, v72
	v_add_u32_e32 v181, 17, v178
	v_cndmask_b32_e32 v64, 1.0, v64, vcc
	v_cmp_lt_i32_e32 vcc, v181, v85
	v_min_f32_e32 v76, 0x42e6d4ca, v155
	s_nop 0
	v_cndmask_b32_e32 v74, 0, v66, vcc
	v_mul_f32_e32 v66, v68, v66
	v_add_f32_e32 v68, 1.0, v72
	v_rcp_f32_e32 v68, v68
	v_exp_f32_e32 v76, v76
	v_add_u32_e32 v182, 18, v178
	v_cndmask_b32_e32 v66, 1.0, v66, vcc
	v_cmp_lt_i32_e32 vcc, v182, v85
	v_add_u32_e32 v183, 19, v178
	v_min_f32_e32 v98, 0x42e6d4ca, v153
	v_cndmask_b32_e32 v92, 0, v68, vcc
	v_mul_f32_e32 v68, v72, v68
	v_add_f32_e32 v72, 1.0, v76
	v_rcp_f32_e32 v72, v72
	v_cndmask_b32_e32 v68, 1.0, v68, vcc
	v_cmp_lt_i32_e32 vcc, v183, v85
	v_exp_f32_e32 v98, v98
	s_nop 0
	v_cndmask_b32_e32 v78, 0, v72, vcc
	v_mul_f32_e32 v72, v76, v72
	v_cndmask_b32_e32 v94, 1.0, v72, vcc
	v_mul_f32_e32 v68, v94, v68
	v_mul_f32_e32 v66, v66, v68
	v_mul_f32_e32 v64, v64, v66
	ds_bpermute_b32 v72, v241, v64
	ds_bpermute_b32 v76, v242, v64
	ds_bpermute_b32 v95, v243, v64
	v_add_u32_e32 v184, 32, v178
	v_cmp_lt_i32_e32 vcc, v184, v85
	s_waitcnt lgkmcnt(2)
	v_cndmask_b32_e64 v93, 1.0, v72, s[14:15]
	s_waitcnt lgkmcnt(1)
	v_cndmask_b32_e64 v96, 1.0, v76, s[16:17]
	v_mul_f32_e32 v93, v93, v96
	v_min_f32_e32 v96, 0x42e6d4ca, v151
	v_exp_f32_e32 v96, v96
	s_waitcnt lgkmcnt(0)
; __device__ __forceinline__ float fexp(float x) { return __builtin_amdgcn_exp2f(x * 1.44269504f); }
; __device__ __forceinline__ void item_attn(const Params& p, int l, int aidx) {
;     ...
; #pragma unroll
;           for (int m = 0; m < 4; ++m) {
;             float f[4];
; #pragma unroll
;             for (int j = 0; j < 4; ++j) {
;               const float e = fexp(fminf(-z[m][n][j], 80.f));
;               const float sg = __builtin_amdgcn_rcpf(1.f + e);
;               if (decltype(MASKED)::value) {
;                 const bool ok = (kt * 64 + m * 16 + fq * 4 + j) < qpos;
;                 wgt[m][j] = ok ? sg : 0.f;
;                 f[j] = ok ? e * sg : 1.f;
;               } else { wgt[m][j] = sg; f[j] = e * sg; }
;             }
;             excl[m][3] = 1.f; excl[m][2] = f[3]; excl[m][1] = f[3] * f[2]; excl[m][0] = excl[m][1] * f[1];
;             const float G = excl[m][0] * f[0];
;             const float g1 = __shfl_xor(G, 16), g2 = __shfl_xor(G, 32), g3 = __shfl_xor(G, 48);
;             later[m] = ((fq ^ 1) > fq ? g1 : 1.f) * ((fq ^ 2) > fq ? g2 : 1.f) * ((fq ^ 3) > fq ? g3 : 1.f);
;             TT[m] = (G * g1) * (g2 * g3);
;           }
	v_cndmask_b32_e64 v97, 1.0, v95, s[18:19]
	v_mul_f32_e32 v93, v97, v93
	v_min_f32_e32 v99, 0x42e6d4ca, v152
	v_add_f32_e32 v97, 1.0, v96
	v_rcp_f32_e32 v97, v97
	v_exp_f32_e32 v99, v99
	v_add_u32_e32 v185, 33, v178
	v_cndmask_b32_e32 v101, 0, v97, vcc
	v_mul_f32_e32 v96, v96, v97
	v_add_f32_e32 v97, 1.0, v98
	v_rcp_f32_e32 v97, v97
	v_cndmask_b32_e32 v96, 1.0, v96, vcc
	v_cmp_lt_i32_e32 vcc, v185, v85
	v_add_u32_e32 v186, 34, v178
	v_mul_f32_e32 v164, v76, v95
	v_cndmask_b32_e32 v169, 0, v97, vcc
	v_mul_f32_e32 v97, v98, v97
	v_add_f32_e32 v98, 1.0, v99
	v_rcp_f32_e32 v100, v98
	v_min_f32_e32 v98, 0x42e6d4ca, v150
	v_exp_f32_e32 v162, v98
	v_cndmask_b32_e32 v97, 1.0, v97, vcc
	v_cmp_lt_i32_e32 vcc, v186, v85
	v_mul_f32_e32 v99, v99, v100
	v_min_f32_e32 v76, 0x42e6d4ca, v147
	v_cndmask_b32_e32 v98, 0, v100, vcc
	v_add_f32_e32 v100, 1.0, v162
	v_rcp_f32_e32 v100, v100
	v_add_u32_e32 v187, 35, v178
	v_cndmask_b32_e32 v99, 1.0, v99, vcc
	v_cmp_lt_i32_e32 vcc, v187, v85
	v_exp_f32_e32 v76, v76
	v_add_u32_e32 v202, 48, v178
	v_cndmask_b32_e32 v199, 0, v100, vcc
	v_mul_f32_e32 v100, v162, v100
	v_cndmask_b32_e32 v100, 1.0, v100, vcc
	v_mul_f32_e32 v200, v100, v99
	v_min_f32_e32 v99, 0x42e6d4ca, v149
	v_add_f32_e32 v95, 1.0, v76
	v_rcp_f32_e32 v95, v95
	v_exp_f32_e32 v99, v99
	v_cmp_lt_i32_e32 vcc, v202, v85
	v_min_f32_e32 v165, 0x42e6d4ca, v148
	v_mul_f32_e32 v76, v76, v95
	v_cndmask_b32_e32 v203, 0, v95, vcc
	v_add_f32_e32 v95, 1.0, v99
	v_rcp_f32_e32 v95, v95
	v_exp_f32_e32 v165, v165
	v_add_u32_e32 v204, 49, v178
	v_cndmask_b32_e32 v76, 1.0, v76, vcc
	v_cmp_lt_i32_e32 vcc, v204, v85
	v_min_f32_e32 v167, 0x42e6d4ca, v146
	s_nop 0
	v_cndmask_b32_e32 v205, 0, v95, vcc
	v_mul_f32_e32 v95, v99, v95
	v_add_f32_e32 v99, 1.0, v165
	v_rcp_f32_e32 v99, v99
	v_exp_f32_e32 v167, v167
	v_add_u32_e32 v206, 50, v178
	v_cndmask_b32_e32 v95, 1.0, v95, vcc
	v_cmp_lt_i32_e32 vcc, v206, v85
	v_add_u32_e32 v207, 51, v178
	v_mul_f32_e32 v201, v97, v200
	v_cndmask_b32_e32 v168, 0, v99, vcc
	v_mul_f32_e32 v99, v165, v99
	v_add_f32_e32 v165, 1.0, v167
	v_rcp_f32_e32 v165, v165
	v_cndmask_b32_e32 v99, 1.0, v99, vcc
	v_cmp_lt_i32_e32 vcc, v207, v85
	v_mul_f32_e32 v97, v96, v201
	ds_bpermute_b32 v163, v241, v97
	v_cndmask_b32_e32 v218, 0, v165, vcc
	v_mul_f32_e32 v165, v167, v165
	v_cndmask_b32_e32 v170, 1.0, v165, vcc
	v_mul_f32_e32 v219, v170, v99
	ds_bpermute_b32 v96, v242, v97
	v_mul_f32_e32 v220, v95, v219
	ds_bpermute_b32 v166, v243, v97
	v_mul_f32_e32 v172, v76, v220
	ds_bpermute_b32 v173, v242, v172
	ds_bpermute_b32 v174, v241, v172
	ds_bpermute_b32 v175, v243, v172
	v_mul_f32_e32 v162, v64, v72
	s_waitcnt lgkmcnt(5)
	v_cndmask_b32_e64 v64, 1.0, v163, s[14:15]
	s_waitcnt lgkmcnt(4)
	v_cndmask_b32_e64 v72, 1.0, v96, s[16:17]
	v_mul_f32_e32 v64, v64, v72
	s_waitcnt lgkmcnt(3)
	v_cndmask_b32_e64 v72, 1.0, v166, s[18:19]
	v_mul_f32_e32 v99, v72, v64
	s_waitcnt lgkmcnt(2)
	v_cndmask_b32_e64 v64, 1.0, v173, s[16:17]
	s_waitcnt lgkmcnt(0)
	v_pk_mul_f32 v[172:173], v[172:173], v[174:175]
	v_mul_f32_e32 v176, v97, v163
	v_mov_b32_e32 v97, v172
	v_mov_b32_e32 v167, v173
	v_pk_mul_f32 v[96:97], v[96:97], v[166:167]
	v_mov_b32_e32 v177, v91
	v_pk_mul_f32 v[166:167], v[176:177], v[96:97]
	v_cndmask_b32_e64 v72, 1.0, v174, s[14:15]
	v_mov_b32_e32 v163, v166
	v_mov_b32_e32 v165, v167
	v_pk_mul_f32 v[96:97], v[162:163], v[164:165]
	v_mul_f32_e32 v64, v72, v64
	v_cndmask_b32_e64 v72, 1.0, v175, s[18:19]
	v_mov_b32_e32 v95, v97
	v_mul_f32_e32 v171, v72, v64
	v_mul_f32_e32 v64, v70, v66
	v_pk_mul_f32 v[92:93], v[92:93], v[94:95]
	v_mul_f32_e32 v66, v74, v68
	v_mul_f32_e32 v95, v64, v93
	v_mul_f32_e32 v64, v101, v201
	v_mov_b32_e32 v101, v167
	v_mul_f32_e32 v163, v66, v93
	v_mul_f32_e32 v165, v92, v93
	v_mul_f32_e32 v176, v78, v93
	v_mul_f32_e32 v66, v169, v200
	v_pk_mul_f32 v[92:93], v[98:99], v[100:101]
	v_mov_b32_e32 v169, v91
	v_min_f32_e32 v78, 0x42e6d4ca, v141
	v_mul_f32_e32 v99, v64, v93
	v_mul_f32_e32 v101, v66, v93
	v_mul_f32_e32 v200, v92, v93
	v_mul_f32_e32 v199, v199, v93
	v_pk_mul_f32 v[92:93], v[168:169], v[170:171]
	v_mul_f32_e32 v66, v205, v219
	v_mul_f32_e32 v205, v92, v93
	v_exp_f32_e32 v92, v78
	v_min_f32_e32 v98, 0x42e6d4ca, v140
	v_exp_f32_e32 v98, v98
	v_add_f32_e32 v94, 1.0, v92
	v_rcp_f32_e32 v94, v94
	v_mul_f32_e32 v64, v203, v220
	v_cmp_lt_i32_e32 vcc, v180, v88
	v_mul_f32_e32 v201, v64, v93
	v_mul_f32_e32 v203, v66, v93
	v_mul_f32_e32 v93, v218, v93
	v_cndmask_b32_e32 v218, 0, v94, vcc
	v_mul_f32_e32 v92, v92, v94
	v_min_f32_e32 v94, 0x42e6d4ca, v139
	v_cndmask_b32_e32 v100, 1.0, v92, vcc
	v_add_f32_e32 v92, 1.0, v98
	v_min_f32_e32 v162, 0x42e6d4ca, v138
	v_rcp_f32_e32 v92, v92
	v_exp_f32_e32 v94, v94
	v_exp_f32_e32 v162, v162
	v_cmp_lt_i32_e32 vcc, v181, v88
	v_min_f32_e32 v64, 0x42e6d4ca, v145
	s_nop 0
	v_cndmask_b32_e32 v219, 0, v92, vcc
	v_mul_f32_e32 v92, v98, v92
	v_add_f32_e32 v98, 1.0, v94
	v_rcp_f32_e32 v98, v98
	v_add_f32_e32 v166, 1.0, v162
	v_rcp_f32_e32 v166, v166
	v_cndmask_b32_e32 v164, 1.0, v92, vcc
	v_cmp_lt_i32_e32 vcc, v182, v88
	v_mul_f32_e32 v94, v94, v98
	v_min_f32_e32 v66, 0x42e6d4ca, v144
	v_cndmask_b32_e32 v92, 0, v98, vcc
	v_cndmask_b32_e32 v98, 1.0, v94, vcc
	v_mul_f32_e32 v94, v162, v166
	v_min_f32_e32 v162, 0x42e6d4ca, v137
	v_cmp_lt_i32_e32 vcc, v183, v88
	v_exp_f32_e32 v162, v162
	v_exp_f32_e32 v68, v64
	v_cndmask_b32_e32 v94, 1.0, v94, vcc
	v_mul_f32_e32 v221, v94, v98
	v_mul_f32_e32 v222, v164, v221
	v_mul_f32_e32 v183, v100, v222
	v_add_f32_e32 v98, 1.0, v162
	v_min_f32_e32 v100, 0x42e6d4ca, v136
	v_rcp_f32_e32 v98, v98
	v_exp_f32_e32 v100, v100
	v_cndmask_b32_e32 v220, 0, v166, vcc
	v_cmp_lt_i32_e32 vcc, v184, v88
; __device__ __forceinline__ float fexp(float x) { return __builtin_amdgcn_exp2f(x * 1.44269504f); }
; __device__ __forceinline__ unsigned pack2(float a, float b) { unsigned r; asm volatile("v_cvt_pk_bf16_f32 %0, %1, %2" : "=v"(r) : "v"(a), "v"(b)); return r; }
; __device__ __forceinline__ void item_attn(const Params& p, int l, int aidx) {
;     ...
; #pragma unroll
;           for (int m = 0; m < 4; ++m) {
;             float f[4];
; #pragma unroll
;             for (int j = 0; j < 4; ++j) {
;               const float e = fexp(fminf(-z[m][n][j], 80.f));
;               const float sg = __builtin_amdgcn_rcpf(1.f + e);
;               if (decltype(MASKED)::value) {
;                 const bool ok = (kt * 64 + m * 16 + fq * 4 + j) < qpos;
;                 wgt[m][j] = ok ? sg : 0.f;
;                 f[j] = ok ? e * sg : 1.f;
;               } else { wgt[m][j] = sg; f[j] = e * sg; }
;             }
;             excl[m][3] = 1.f; excl[m][2] = f[3]; excl[m][1] = f[3] * f[2]; excl[m][0] = excl[m][1] * f[1];
;             const float G = excl[m][0] * f[0];
;             const float g1 = __shfl_xor(G, 16), g2 = __shfl_xor(G, 32), g3 = __shfl_xor(G, 48);
;             later[m] = ((fq ^ 1) > fq ? g1 : 1.f) * ((fq ^ 2) > fq ? g2 : 1.f) * ((fq ^ 3) > fq ? g3 : 1.f);
;             TT[m] = (G * g1) * (g2 * g3);
;           }
;           float lm[4]; lm[3] = carry[n]; lm[2] = lm[3] * TT[3]; lm[1] = lm[2] * TT[2]; lm[0] = lm[1] * TT[1];
; #pragma unroll
;           for (int m = 0; m < 4; ++m) {
;             const float base = later[m] * lm[m];
;             float pv[4];
; #pragma unroll
;             for (int j = 0; j < 4; ++j) pv[j] = wgt[m][j] * excl[m][j] * base;
;             pk[m][n][0] = pack2(pv[0], pv[1]); pk[m][n][1] = pack2(pv[2], pv[3]);
;           }
;           carry[n] = lm[0] * TT[0];
	v_min_f32_e32 v164, 0x42e6d4ca, v135
	s_nop 0
	v_cndmask_b32_e32 v184, 0, v98, vcc
	v_mul_f32_e32 v98, v162, v98
	v_cndmask_b32_e32 v162, 1.0, v98, vcc
	v_add_f32_e32 v98, 1.0, v100
	v_min_f32_e32 v166, 0x42e6d4ca, v134
	v_rcp_f32_e32 v98, v98
	v_exp_f32_e32 v164, v164
	v_exp_f32_e32 v166, v166
	v_cmp_lt_i32_e32 vcc, v185, v88
	v_exp_f32_e32 v66, v66
	s_nop 0
	v_cndmask_b32_e32 v185, 0, v98, vcc
	v_mul_f32_e32 v98, v100, v98
	v_add_f32_e32 v100, 1.0, v164
	v_rcp_f32_e32 v100, v100
	v_add_f32_e32 v168, 1.0, v166
	v_rcp_f32_e32 v168, v168
	v_cndmask_b32_e32 v167, 1.0, v98, vcc
	v_cmp_lt_i32_e32 vcc, v186, v88
	v_add_f32_e32 v64, 1.0, v68
	v_min_f32_e32 v70, 0x42e6d4ca, v142
	v_cndmask_b32_e32 v98, 0, v100, vcc
	v_mul_f32_e32 v100, v164, v100
	v_cndmask_b32_e32 v164, 1.0, v100, vcc
	v_mul_f32_e32 v100, v166, v168
	v_min_f32_e32 v166, 0x42e6d4ca, v132
	v_cmp_lt_i32_e32 vcc, v187, v88
	v_exp_f32_e32 v166, v166
	v_rcp_f32_e32 v72, v64
	v_cndmask_b32_e32 v100, 1.0, v100, vcc
	v_mul_f32_e32 v187, v100, v164
	v_mul_f32_e32 v223, v167, v187
	v_mul_f32_e32 v224, v162, v223
	v_add_f32_e32 v162, 1.0, v166
	v_min_f32_e32 v164, 0x42e6d4ca, v133
	v_rcp_f32_e32 v162, v162
	v_exp_f32_e32 v164, v164
	v_cndmask_b32_e32 v186, 0, v168, vcc
	v_cmp_lt_i32_e32 vcc, v202, v88
	v_add_f32_e32 v64, 1.0, v66
	v_min_f32_e32 v168, 0x42e6d4ca, v130
	v_cndmask_b32_e32 v202, 0, v162, vcc
	v_mul_f32_e32 v162, v166, v162
	v_min_f32_e32 v166, 0x42e6d4ca, v131
	v_cndmask_b32_e32 v167, 1.0, v162, vcc
	v_add_f32_e32 v162, 1.0, v164
	v_rcp_f32_e32 v162, v162
	v_exp_f32_e32 v166, v166
	v_rcp_f32_e32 v74, v64
	v_min_f32_e32 v64, 0x42e6d4ca, v143
	v_exp_f32_e32 v70, v70
	v_exp_f32_e32 v168, v168
	v_exp_f32_e32 v64, v64
	v_cmp_lt_i32_e32 vcc, v204, v88
	v_add_f32_e32 v76, 1.0, v70
	v_add_f32_e32 v169, 1.0, v168
	v_cndmask_b32_e32 v204, 0, v162, vcc
	v_mul_f32_e32 v162, v164, v162
	v_add_f32_e32 v164, 1.0, v166
	v_rcp_f32_e32 v164, v164
	v_add_f32_e32 v79, 1.0, v71
	v_rcp_f32_e32 v78, v76
	v_add_f32_e32 v76, 1.0, v64
	v_rcp_f32_e32 v169, v169
	v_rcp_f32_e32 v79, v79
	v_rcp_f32_e32 v76, v76
	v_cndmask_b32_e32 v180, 1.0, v162, vcc
	v_cmp_lt_i32_e32 vcc, v206, v88
	v_add_u32_e32 v179, 1, v178
	v_pk_mul_f32 v[70:71], v[70:71], v[78:79]
	v_cndmask_b32_e32 v162, 0, v164, vcc
	v_mul_f32_e32 v164, v166, v164
	v_cndmask_b32_e32 v166, 1.0, v164, vcc
	v_cmp_lt_i32_e32 vcc, v207, v88
	v_mul_f32_e32 v164, v168, v169
	v_or_b32_e32 v168, 3, v178
	v_cndmask_b32_e32 v206, 0, v169, vcc
	v_or_b32_e32 v169, 2, v178
	v_cndmask_b32_e32 v164, 1.0, v164, vcc
	v_cmp_lt_i32_e64 s[24:25], v169, v85
	v_cmp_lt_i32_e64 s[26:27], v168, v85
	v_pk_mul_f32 v[64:65], v[64:65], v[76:77]
	v_mul_f32_e32 v207, v164, v166
	v_cmp_lt_i32_e64 s[22:23], v179, v85
	v_cndmask_b32_e64 v166, 0, v77, s[24:25]
	v_cndmask_b32_e64 v227, 0, v79, s[26:27]
	v_pk_mul_f32 v[66:67], v[66:67], v[74:75]
	v_cndmask_b32_e64 v71, 1.0, v71, s[26:27]
	v_cmp_lt_i32_e64 s[26:27], v169, v88
	v_cndmask_b32_e64 v169, 1.0, v65, s[24:25]
	v_cmp_lt_i32_e64 s[24:25], v168, v88
	v_cmp_lt_i32_e32 vcc, v178, v85
	v_cndmask_b32_e64 v226, 0, v75, s[22:23]
	v_pk_mul_f32 v[68:69], v[68:69], v[72:73]
	v_cndmask_b32_e64 v67, 1.0, v67, s[22:23]
	v_cmp_lt_i32_e64 s[22:23], v179, v88
	v_cndmask_b32_e64 v70, 1.0, v70, s[26:27]
	v_cndmask_b32_e64 v168, 1.0, v64, s[24:25]
	v_cndmask_b32_e32 v225, 0, v73, vcc
	v_cndmask_b32_e32 v69, 1.0, v69, vcc
	v_cmp_lt_i32_e32 vcc, v178, v88
	v_cndmask_b32_e64 v66, 1.0, v66, s[22:23]
	v_pk_mul_f32 v[170:171], v[70:71], v[168:169]
	v_cndmask_b32_e32 v68, 1.0, v68, vcc
	v_pk_mul_f32 v[172:173], v[66:67], v[170:171]
	v_mul_f32_e32 v228, v180, v207
	v_pk_mul_f32 v[174:175], v[68:69], v[172:173]
	ds_bpermute_b32 v177, v241, v175
	ds_bpermute_b32 v179, v242, v175
	ds_bpermute_b32 v181, v243, v175
	v_pk_mul_f32 v[96:97], v[96:97], v[96:97] op_sel:[0,1] op_sel_hi:[1,0]
	v_mul_f32_e32 v182, v167, v228
	s_waitcnt lgkmcnt(2)
	v_cndmask_b32_e64 v64, 1.0, v177, s[14:15]
	s_waitcnt lgkmcnt(1)
	v_cndmask_b32_e64 v65, 1.0, v179, s[16:17]
	v_mul_f32_e32 v64, v64, v65
	s_waitcnt lgkmcnt(0)
; __device__ __forceinline__ unsigned pack2(float a, float b) { unsigned r; asm volatile("v_cvt_pk_bf16_f32 %0, %1, %2" : "=v"(r) : "v"(a), "v"(b)); return r; }
; __device__ __forceinline__ void item_attn(const Params& p, int l, int aidx) {
;     ...
;             excl[m][3] = 1.f; excl[m][2] = f[3]; excl[m][1] = f[3] * f[2]; excl[m][0] = excl[m][1] * f[1];
;             const float G = excl[m][0] * f[0];
;             const float g1 = __shfl_xor(G, 16), g2 = __shfl_xor(G, 32), g3 = __shfl_xor(G, 48);
;             later[m] = ((fq ^ 1) > fq ? g1 : 1.f) * ((fq ^ 2) > fq ? g2 : 1.f) * ((fq ^ 3) > fq ? g3 : 1.f);
;             TT[m] = (G * g1) * (g2 * g3);
;           }
;           float lm[4]; lm[3] = carry[n]; lm[2] = lm[3] * TT[3]; lm[1] = lm[2] * TT[2]; lm[0] = lm[1] * TT[1];
; #pragma unroll
;           for (int m = 0; m < 4; ++m) {
;             const float base = later[m] * lm[m];
;             float pv[4];
; #pragma unroll
;             for (int j = 0; j < 4; ++j) pv[j] = wgt[m][j] * excl[m][j] * base;
;             pk[m][n][0] = pack2(pv[0], pv[1]); pk[m][n][1] = pack2(pv[2], pv[3]);
;           }
;           carry[n] = lm[0] * TT[0];
;         }
;       };
;       if (kt * 64 + 63 < qpos0 + 32 * wid) sb_weights(std::false_type{}); else sb_weights(std::true_type{});
	v_cndmask_b32_e64 v65, 1.0, v181, s[18:19]
	v_mul_f32_e32 v167, v65, v64
	v_pk_mov_b32 v[64:65], v[70:71], v[96:97] op_sel:[1,0]
	v_mul_f32_e32 v66, v225, v173
	v_mul_f32_e32 v67, v226, v171
	v_pk_mul_f32 v[64:65], v[166:167], v[64:65]
	ds_bpermute_b32 v178, v242, v174
	v_mul_f32_e32 v66, v66, v65
	v_mul_f32_e32 v67, v67, v65
	v_mul_f32_e32 v64, v64, v65
	v_mul_f32_e32 v65, v227, v65
	v_cvt_pk_bf16_f32 v68, v66, v67
	v_cvt_pk_bf16_f32 v69, v64, v65
	v_cvt_pk_bf16_f32 v70, v95, v163
	v_cvt_pk_bf16_f32 v71, v165, v176
	ds_bpermute_b32 v176, v241, v174
	ds_bpermute_b32 v180, v243, v174
	ds_bpermute_b32 v75, v241, v183
	ds_bpermute_b32 v77, v242, v183
	ds_bpermute_b32 v79, v243, v183
	v_cndmask_b32_e64 v97, 0, v74, s[22:23]
	s_waitcnt lgkmcnt(4)
	v_cndmask_b32_e64 v73, 1.0, v176, s[14:15]
	v_cndmask_b32_e64 v74, 1.0, v178, s[16:17]
	v_mul_f32_e32 v73, v73, v74
	s_waitcnt lgkmcnt(3)
	v_cndmask_b32_e64 v74, 1.0, v180, s[18:19]
	v_cvt_pk_bf16_f32 v64, v99, v101
	v_cndmask_b32_e64 v101, 0, v76, s[24:25]
	v_mul_f32_e32 v73, v74, v73
	s_waitcnt lgkmcnt(2)
	v_cndmask_b32_e64 v74, 1.0, v75, s[14:15]
	s_waitcnt lgkmcnt(1)
	v_cndmask_b32_e64 v76, 1.0, v77, s[16:17]
	v_mul_f32_e32 v74, v74, v76
	s_waitcnt lgkmcnt(0)
	v_cndmask_b32_e64 v76, 1.0, v79, s[18:19]
	v_cvt_pk_bf16_f32 v65, v200, v199
	v_cvt_pk_bf16_f32 v66, v201, v203
	v_cvt_pk_bf16_f32 v67, v205, v93
	v_mul_f32_e32 v93, v76, v74
	ds_bpermute_b32 v163, v241, v224
	ds_bpermute_b32 v74, v242, v224
	v_cndmask_b32_e32 v95, 0, v72, vcc
	v_cndmask_b32_e64 v72, 0, v78, s[26:27]
	ds_bpermute_b32 v78, v243, v224
	v_pk_mul_f32 v[166:167], v[174:175], v[176:177]
	v_mul_f32_e32 v76, v183, v75
	ds_bpermute_b32 v183, v242, v182
	ds_bpermute_b32 v176, v241, v182
	ds_bpermute_b32 v177, v243, v182
	v_pk_mul_f32 v[174:175], v[178:179], v[180:181]
	s_waitcnt lgkmcnt(5)
	v_cndmask_b32_e64 v75, 1.0, v163, s[14:15]
	v_pk_mul_f32 v[166:167], v[166:167], v[174:175]
	v_mul_f32_e32 v174, v77, v79
	s_waitcnt lgkmcnt(4)
	v_cndmask_b32_e64 v77, 1.0, v74, s[16:17]
	v_mul_f32_e32 v75, v75, v77
	s_waitcnt lgkmcnt(3)
	v_cndmask_b32_e64 v77, 1.0, v78, s[18:19]
	v_mul_f32_e32 v99, v77, v75
	s_waitcnt lgkmcnt(2)
	v_cndmask_b32_e64 v75, 1.0, v183, s[16:17]
	s_waitcnt lgkmcnt(1)
	v_cndmask_b32_e64 v77, 1.0, v176, s[14:15]
	v_mul_f32_e32 v75, v77, v75
	s_waitcnt lgkmcnt(0)
	v_cndmask_b32_e64 v77, 1.0, v177, s[18:19]
	v_pk_mul_f32 v[176:177], v[182:183], v[176:177]
	v_mul_f32_e32 v165, v77, v75
	v_mov_b32_e32 v75, v176
	v_mov_b32_e32 v79, v177
	v_mul_f32_e32 v178, v224, v163
	v_pk_mul_f32 v[74:75], v[74:75], v[78:79]
	v_mov_b32_e32 v179, v90
	v_pk_mul_f32 v[78:79], v[178:179], v[74:75]
	v_mov_b32_e32 v163, v90
	v_mov_b32_e32 v77, v78
	v_mov_b32_e32 v175, v79
	v_pk_mul_f32 v[74:75], v[76:77], v[174:175]
	v_mul_f32_e32 v76, v97, v170
	v_pk_mul_f32 v[174:175], v[74:75], v[74:75] op_sel:[0,1] op_sel_hi:[1,0]
	v_mul_f32_e32 v74, v95, v172
	v_mov_b32_e32 v169, v174
	v_pk_mul_f32 v[72:73], v[72:73], v[168:169]
	v_mov_b32_e32 v95, v75
	v_mul_f32_e32 v74, v74, v73
	v_mul_f32_e32 v76, v76, v73
	v_mul_f32_e32 v77, v72, v73
	v_mul_f32_e32 v73, v101, v73
	v_cvt_pk_bf16_f32 v72, v74, v76
	v_cvt_pk_bf16_f32 v73, v77, v73
	v_mul_f32_e32 v76, v218, v222
	v_mul_f32_e32 v77, v219, v221
	v_pk_mul_f32 v[74:75], v[92:93], v[94:95]
	v_mov_b32_e32 v101, v79
	v_mul_f32_e32 v76, v76, v75
	v_mul_f32_e32 v77, v77, v75
	v_mul_f32_e32 v78, v74, v75
	v_mul_f32_e32 v75, v220, v75
	v_cvt_pk_bf16_f32 v74, v76, v77
	v_cvt_pk_bf16_f32 v75, v78, v75
	v_mul_f32_e32 v78, v184, v223
	v_mul_f32_e32 v92, v185, v187
	v_pk_mul_f32 v[76:77], v[98:99], v[100:101]
	v_mul_f32_e32 v93, v204, v207
	v_mul_f32_e32 v78, v78, v77
	v_mul_f32_e32 v79, v92, v77
	v_mul_f32_e32 v92, v76, v77
	v_mul_f32_e32 v77, v186, v77
	v_cvt_pk_bf16_f32 v76, v78, v79
	v_cvt_pk_bf16_f32 v77, v92, v77
	v_mul_f32_e32 v92, v202, v228
	v_pk_mul_f32 v[78:79], v[162:163], v[164:165]
	v_mov_b32_e32 v175, v96
	v_mul_f32_e32 v92, v92, v79
	v_mul_f32_e32 v93, v93, v79
	v_mul_f32_e32 v94, v78, v79
	v_mul_f32_e32 v79, v206, v79
	v_cvt_pk_bf16_f32 v78, v92, v93
	v_pk_mul_f32 v[92:93], v[166:167], v[174:175]
	s_mov_b64 s[0:1], 0
	v_cvt_pk_bf16_f32 v79, v94, v79
